# P10 epilogue: f32 output stores coalesced to 64B row segments via permlane16/32 swaps
# baseline (speedup 1.0000x reference)
; #define LAS __attribute__((address_space(3)))
; DI unsigned f2bf(float f) { return pk2(f, 0.f) & 0xffffu; }
; #define MFMA32(a, b, c) __builtin_amdgcn_mfma_f32_32x32x16_bf16((a), (b), (c), 0, 0, 0)
; template <int BR, int NT, int DV> ...
;     ...
;     for (int ti = 0; ti < NT; ++ti) {
;         LAS unsigned char* kb = ti ? kbB : kbA; const int j = ti ? jB : jA;
; #pragma unroll
;         for (int i = 0; i < 16; ++i) { s[2 * ti][i] = 0.f; s[2 * ti + 1][i] = 0.f; }
; #pragma unroll
;         for (int ks = 0; ks < ((DV & 4) ? 0 : 4); ++ks) {
;             const bf16x8 a0 = *(const LAS bf16x8*)(kb + c.n * 144 + ks * 32 + c.h * 16);
;             const bf16x8 a1 = *(const LAS bf16x8*)(kb + (32 + c.n) * 144 + ks * 32 + c.h * 16);
;             s[2 * ti] = MFMA32(a0, c.qf[ks], s[2 * ti]); s[2 * ti + 1] = MFMA32(a1, c.qf[ks], s[2 * ti + 1]);
;         }
;         {
;             const int pos0 = (BR <= 1) ? (1024 * j + 31 - c.t) : (64 * j - c.t);
;             float tb = c.slope2 * (float)pos0;
;             if (BR == 2) { if (!m128_bit(c.sel_lo, c.sel_hi, j)) tb = -1e30f; }
;             const unsigned thi = f2bf(tb); const unsigned tlo = f2bf(tb - bf2f(thi));
;             u32x4 bw = (u32x4){(BR <= 1) ? c.slope16w : c.slopew, thi | (tlo << 16), 0u, 0u};
;             if (c.h) bw = (u32x4){0u, 0u, 0u, 0u};
;             const bf16x8 bb = __builtin_bit_cast(bf16x8, bw);
;             s[2 * ti] = MFMA32(c.akey[0], bb, s[2 * ti]); s[2 * ti + 1] = MFMA32(c.akey[1], bb, s[2 * ti + 1]);
;         }
;         bool bnd;
;         if (BR <= 1) bnd = (64 * j + 63 > 4 * qb - 2); else if (BR == 2) bnd = (j == qb); else bnd = (j == qb) || (j + 8 == qb);
;         if (bnd) {
;             asm volatile("" ::: "memory");
;             const int d0 = (BR <= 1) ? (c.t - 31 - 1024 * j) : (c.t - 64 * j);
; #pragma unroll
;             for (int kt = 0; kt < 2; ++kt)
; #pragma unroll
;                 for (int rr = 0; rr < 16; ++rr) {
;                     const int key = kt * 32 + (rr & 3) + 8 * (rr >> 2) + 4 * c.h;
;                     const int dist = (BR <= 1) ? (d0 - 16 * key) : (d0 - key);
;                     bool valid = dist >= 0;
;                     if (BR == 3) valid = valid && (dist < 512);
;                     s[2 * ti + kt][rr] = valid ? s[2 * ti + kt][rr] : -INFINITY;
;                 }
;         }
.LBB0_1018:
	s_andn2_saveexec_b64 s[10:11], s[10:11]
	s_cbranch_execz .LBB0_1029
	v_add_u32_e32 v1, s23, v217
	v_add_u32_e32 v4, v1, v162
	ds_read_b128 v[6:9], v4 offset:4608
	ds_read_b128 v[10:13], v4
	ds_read_b128 v[80:83], v4 offset:32
	s_lshl_b32 s17, s22, 6
	v_sub_u32_e32 v1, s17, v209
	s_waitcnt lgkmcnt(2)
	v_mfma_f32_32x32x16_bf16 v[48:63], v[6:9], v[112:115], 0
	ds_read_b128 v[6:9], v4 offset:4640
	v_cvt_f32_i32_e32 v1, v1
	s_cmp_lg_u32 s22, s93
	v_mul_f32_e32 v3, v210, v1
	v_lshrrev_b64 v[0:1], v0, v[144:145]
	s_waitcnt lgkmcnt(2)
	v_mfma_f32_32x32x16_bf16 v[64:79], v[10:13], v[112:115], 0
	s_waitcnt lgkmcnt(1)
	v_mfma_f32_32x32x16_bf16 v[64:79], v[80:83], v[116:119], v[64:79]
	s_waitcnt lgkmcnt(0)
	v_mfma_f32_32x32x16_bf16 v[48:63], v[6:9], v[116:119], v[48:63]
	ds_read_b128 v[6:9], v4 offset:64
	ds_read_b128 v[10:13], v4 offset:4672
	s_waitcnt lgkmcnt(1)
	v_mfma_f32_32x32x16_bf16 v[64:79], v[6:9], v[120:123], v[64:79]
	s_waitcnt lgkmcnt(0)
	v_mfma_f32_32x32x16_bf16 v[48:63], v[10:13], v[120:123], v[48:63]
	ds_read_b128 v[6:9], v4 offset:96
	ds_read_b128 v[10:13], v4 offset:4704
	s_waitcnt lgkmcnt(1)
	v_mfma_f32_32x32x16_bf16 v[64:79], v[6:9], v[124:127], v[64:79]
	v_lshrrev_b64 v[6:7], s22, v[142:143]
	v_cndmask_b32_e64 v0, v0, v6, s[8:9]
	v_and_b32_e32 v0, 1, v0
	v_cmp_eq_u32_e32 vcc, 1, v0
	s_nop 1
	v_cndmask_b32_e32 v0, v207, v3, vcc
	s_waitcnt lgkmcnt(0)
	v_mfma_f32_32x32x16_bf16 v[48:63], v[10:13], v[124:127], v[48:63]
	v_cvt_pk_bf16_f32 v1, v0, 0
	v_and_b32_e32 v3, 0xffff, v1
	v_lshlrev_b32_e32 v1, 16, v1
	v_sub_f32_e32 v0, v0, v1
	v_cvt_pk_bf16_f32 v0, v0, 0
	v_lshl_or_b32 v0, v0, 16, v3
	v_cndmask_b32_e64 v1, 0, v0, s[6:7]
	v_cndmask_b32_e64 v0, 0, v136, s[6:7]
	v_mov_b32_e32 v3, v2
	s_nop 1
	v_mfma_f32_32x32x16_bf16 v[64:79], v[128:131], v[0:3], v[64:79]
	v_mfma_f32_32x32x16_bf16 v[48:63], v[132:135], v[0:3], v[48:63]
	s_cbranch_scc1 .LBB0_1021
	v_or_b32_e32 v1, s17, v218
	v_cmp_ge_i32_e32 vcc, v209, v1
	v_or_b32_e32 v3, s17, v221
	v_or_b32_e32 v5, s17, v222
	s_nop 5
	v_cndmask_b32_e32 v64, v203, v64, vcc
	v_cmp_lt_i32_e32 vcc, v1, v209
	v_or_b32_e32 v6, s17, v223
	s_nop 0
	v_cndmask_b32_e32 v65, v203, v65, vcc
	v_cmp_ge_i32_e32 vcc, v219, v1
	s_nop 1
	v_cndmask_b32_e32 v66, v203, v66, vcc
	v_cmp_ge_i32_e32 vcc, v220, v1
	s_nop 1
	v_cndmask_b32_e32 v67, v203, v67, vcc
	v_cmp_ge_i32_e32 vcc, v209, v3
	s_nop 1
	v_cndmask_b32_e32 v68, v203, v68, vcc
	v_cmp_lt_i32_e32 vcc, v3, v209
	s_nop 1
	v_cndmask_b32_e32 v69, v203, v69, vcc
	v_cmp_ge_i32_e32 vcc, v219, v3
	s_nop 1
	v_cndmask_b32_e32 v70, v203, v70, vcc
	v_cmp_ge_i32_e32 vcc, v220, v3
	s_nop 1
	v_cndmask_b32_e32 v71, v203, v71, vcc
	v_cmp_ge_i32_e32 vcc, v209, v5
	s_nop 1
	v_cndmask_b32_e32 v72, v203, v72, vcc
	v_cmp_lt_i32_e32 vcc, v5, v209
	s_nop 1
	v_cndmask_b32_e32 v73, v203, v73, vcc
	v_cmp_ge_i32_e32 vcc, v219, v5
	s_nop 1
	v_cndmask_b32_e32 v74, v203, v74, vcc
	v_cmp_ge_i32_e32 vcc, v220, v5
	s_nop 1
	v_cndmask_b32_e32 v75, v203, v75, vcc
	v_cmp_ge_i32_e32 vcc, v209, v6
	s_nop 1
	v_cndmask_b32_e32 v76, v203, v76, vcc
	v_cmp_lt_i32_e32 vcc, v6, v209
	s_nop 1
	v_cndmask_b32_e32 v77, v203, v77, vcc
	v_cmp_ge_i32_e32 vcc, v219, v6
	s_nop 1
	v_cndmask_b32_e32 v78, v203, v78, vcc
	v_cmp_ge_i32_e32 vcc, v220, v6
	s_nop 1
	v_cndmask_b32_e32 v79, v203, v79, vcc
	v_cmp_ge_i32_e32 vcc, v224, v1
	s_nop 1
	v_cndmask_b32_e32 v48, v203, v48, vcc
	v_cmp_ge_i32_e32 vcc, v225, v1
	s_nop 1
	v_cndmask_b32_e32 v49, v203, v49, vcc
	v_cmp_ge_i32_e32 vcc, v226, v1
	s_nop 1
	v_cndmask_b32_e32 v50, v203, v50, vcc
	v_cmp_ge_i32_e32 vcc, v227, v1
	s_nop 1
	v_cndmask_b32_e32 v51, v203, v51, vcc
	v_cmp_ge_i32_e32 vcc, v224, v3
	s_nop 1
	v_cndmask_b32_e32 v52, v203, v52, vcc
	v_cmp_ge_i32_e32 vcc, v225, v3
	s_nop 1
	v_cndmask_b32_e32 v53, v203, v53, vcc
	v_cmp_ge_i32_e32 vcc, v226, v3
	s_nop 1
	v_cndmask_b32_e32 v54, v203, v54, vcc
	v_cmp_ge_i32_e32 vcc, v227, v3
	s_nop 1
	v_cndmask_b32_e32 v55, v203, v55, vcc
	v_cmp_ge_i32_e32 vcc, v224, v5
	s_nop 1
	v_cndmask_b32_e32 v56, v203, v56, vcc
	v_cmp_ge_i32_e32 vcc, v225, v5
	s_nop 1
	v_cndmask_b32_e32 v57, v203, v57, vcc
	v_cmp_ge_i32_e32 vcc, v226, v5
	s_nop 1
	v_cndmask_b32_e32 v58, v203, v58, vcc
	v_cmp_ge_i32_e32 vcc, v227, v5
	s_nop 1
	v_cndmask_b32_e32 v59, v203, v59, vcc
	v_cmp_ge_i32_e32 vcc, v224, v6
	s_nop 1
	v_cndmask_b32_e32 v60, v203, v60, vcc
	v_cmp_ge_i32_e32 vcc, v225, v6
	s_nop 1
	v_cndmask_b32_e32 v61, v203, v61, vcc
	v_cmp_ge_i32_e32 vcc, v226, v6
	s_nop 1
	v_cndmask_b32_e32 v62, v203, v62, vcc
	v_cmp_ge_i32_e32 vcc, v227, v6
	s_nop 1
	v_cndmask_b32_e32 v63, v203, v63, vcc
; #define LAS __attribute__((address_space(3)))
; DI unsigned f2bf(float f) { return pk2(f, 0.f) & 0xffffu; }
; #define MFMA32(a, b, c) __builtin_amdgcn_mfma_f32_32x32x16_bf16((a), (b), (c), 0, 0, 0)
; template <int BR, int NT, int DV> ...
;     ...
;     for (int ti = 0; ti < NT; ++ti) {
;         LAS unsigned char* kb = ti ? kbB : kbA; const int j = ti ? jB : jA;
; #pragma unroll
;         for (int i = 0; i < 16; ++i) { s[2 * ti][i] = 0.f; s[2 * ti + 1][i] = 0.f; }
; #pragma unroll
;         for (int ks = 0; ks < ((DV & 4) ? 0 : 4); ++ks) {
;             const bf16x8 a0 = *(const LAS bf16x8*)(kb + c.n * 144 + ks * 32 + c.h * 16);
;             const bf16x8 a1 = *(const LAS bf16x8*)(kb + (32 + c.n) * 144 + ks * 32 + c.h * 16);
;             s[2 * ti] = MFMA32(a0, c.qf[ks], s[2 * ti]); s[2 * ti + 1] = MFMA32(a1, c.qf[ks], s[2 * ti + 1]);
;         }
;         {
;             const int pos0 = (BR <= 1) ? (1024 * j + 31 - c.t) : (64 * j - c.t);
;             float tb = c.slope2 * (float)pos0;
;             if (BR == 2) { if (!m128_bit(c.sel_lo, c.sel_hi, j)) tb = -1e30f; }
;             const unsigned thi = f2bf(tb); const unsigned tlo = f2bf(tb - bf2f(thi));
;             u32x4 bw = (u32x4){(BR <= 1) ? c.slope16w : c.slopew, thi | (tlo << 16), 0u, 0u};
;             if (c.h) bw = (u32x4){0u, 0u, 0u, 0u};
;             const bf16x8 bb = __builtin_bit_cast(bf16x8, bw);
;             s[2 * ti] = MFMA32(c.akey[0], bb, s[2 * ti]); s[2 * ti + 1] = MFMA32(c.akey[1], bb, s[2 * ti + 1]);
;         }
;         bool bnd;
;         if (BR <= 1) bnd = (64 * j + 63 > 4 * qb - 2); else if (BR == 2) bnd = (j == qb); else bnd = (j == qb) || (j + 8 == qb);
;         if (bnd) {
;             asm volatile("" ::: "memory");
;             const int d0 = (BR <= 1) ? (c.t - 31 - 1024 * j) : (c.t - 64 * j);
; #pragma unroll
;             for (int kt = 0; kt < 2; ++kt)
; #pragma unroll
;                 for (int rr = 0; rr < 16; ++rr) {
;                     const int key = kt * 32 + (rr & 3) + 8 * (rr >> 2) + 4 * c.h;
;                     const int dist = (BR <= 1) ? (d0 - 16 * key) : (d0 - key);
;                     bool valid = dist >= 0;
;                     if (BR == 3) valid = valid && (dist < 512);
;                     s[2 * ti + kt][rr] = valid ? s[2 * ti + kt][rr] : -INFINITY;
;                 }
;         }
.LBB0_1021:
	ds_read_b128 v[6:9], v4 offset:13824
	ds_read_b128 v[10:13], v4 offset:9216
	ds_read_b128 v[172:175], v4 offset:9248
	s_lshl_b32 s8, s20, 6
	v_sub_u32_e32 v1, s8, v209
	s_waitcnt lgkmcnt(2)
	v_mfma_f32_32x32x16_bf16 v[80:95], v[6:9], v[112:115], 0
	ds_read_b128 v[6:9], v4 offset:13856
	s_cmp_lt_i32 s20, 64
	v_cvt_f32_i32_e32 v1, v1
	s_cselect_b64 vcc, -1, 0
	s_sub_i32 s9, s20, 64
	s_cmp_lg_u32 s20, s93
	v_mul_f32_e32 v1, v210, v1
	s_waitcnt lgkmcnt(2)
	v_mfma_f32_32x32x16_bf16 v[96:111], v[10:13], v[112:115], 0
	s_waitcnt lgkmcnt(1)
	v_mfma_f32_32x32x16_bf16 v[96:111], v[172:175], v[116:119], v[96:111]
	s_waitcnt lgkmcnt(0)
	v_mfma_f32_32x32x16_bf16 v[80:95], v[6:9], v[116:119], v[80:95]
	ds_read_b128 v[6:9], v4 offset:9280
	ds_read_b128 v[10:13], v4 offset:13888
	s_waitcnt lgkmcnt(1)
	v_mfma_f32_32x32x16_bf16 v[96:111], v[6:9], v[120:123], v[96:111]
	s_waitcnt lgkmcnt(0)
	v_mfma_f32_32x32x16_bf16 v[80:95], v[10:13], v[120:123], v[80:95]
	ds_read_b128 v[6:9], v4 offset:9312
	ds_read_b128 v[10:13], v4 offset:13920
	v_lshrrev_b64 v[4:5], s20, v[142:143]
	s_waitcnt lgkmcnt(1)
	v_mfma_f32_32x32x16_bf16 v[96:111], v[6:9], v[124:127], v[96:111]
	v_lshrrev_b64 v[6:7], s9, v[144:145]
	v_cndmask_b32_e32 v3, v6, v4, vcc
	v_and_b32_e32 v3, 1, v3
	v_cmp_eq_u32_e32 vcc, 1, v3
	s_nop 1
	v_cndmask_b32_e32 v1, v207, v1, vcc
	s_waitcnt lgkmcnt(0)
	v_mfma_f32_32x32x16_bf16 v[80:95], v[10:13], v[124:127], v[80:95]
	v_cvt_pk_bf16_f32 v3, v1, 0
	v_and_b32_e32 v4, 0xffff, v3
	v_lshlrev_b32_e32 v3, 16, v3
	v_sub_f32_e32 v1, v1, v3
	v_cvt_pk_bf16_f32 v1, v1, 0
	v_lshl_or_b32 v1, v1, 16, v4
	v_cndmask_b32_e64 v1, 0, v1, s[6:7]
	v_mov_b32_e32 v3, v2
	s_nop 1
	v_mfma_f32_32x32x16_bf16 v[96:111], v[128:131], v[0:3], v[96:111]
	v_mfma_f32_32x32x16_bf16 v[80:95], v[132:135], v[0:3], v[80:95]
	s_cbranch_scc1 .LBB0_1023
	v_or_b32_e32 v0, s8, v218
	v_sub_u32_e32 v1, v209, v0
	v_cmp_lt_i32_e32 vcc, -1, v1
	v_sub_u32_e32 v1, v0, v209
	s_nop 5
	v_cndmask_b32_e32 v96, v203, v96, vcc
	v_cmp_gt_i32_e32 vcc, 0, v1
	v_sub_u32_e32 v1, v219, v0
	s_nop 0
	v_cndmask_b32_e32 v97, v203, v97, vcc
	v_cmp_lt_i32_e32 vcc, -1, v1
	v_sub_u32_e32 v1, v220, v0
	s_nop 0
	v_cndmask_b32_e32 v98, v203, v98, vcc
	v_cmp_lt_i32_e32 vcc, -1, v1
	v_or_b32_e32 v1, s8, v221
	v_sub_u32_e32 v3, v209, v1
	v_cndmask_b32_e32 v99, v203, v99, vcc
	v_cmp_lt_i32_e32 vcc, -1, v3
	v_sub_u32_e32 v3, v1, v209
	s_nop 0
	v_cndmask_b32_e32 v100, v203, v100, vcc
	v_cmp_gt_i32_e32 vcc, 0, v3
	v_sub_u32_e32 v3, v219, v1
	s_nop 0
	v_cndmask_b32_e32 v101, v203, v101, vcc
	v_cmp_lt_i32_e32 vcc, -1, v3
	v_sub_u32_e32 v3, v220, v1
	s_nop 0
	v_cndmask_b32_e32 v102, v203, v102, vcc
	v_cmp_lt_i32_e32 vcc, -1, v3
	v_or_b32_e32 v3, s8, v222
	v_sub_u32_e32 v4, v209, v3
	v_cndmask_b32_e32 v103, v203, v103, vcc
	v_cmp_lt_i32_e32 vcc, -1, v4
	v_sub_u32_e32 v4, v3, v209
	s_nop 0
	v_cndmask_b32_e32 v104, v203, v104, vcc
	v_cmp_gt_i32_e32 vcc, 0, v4
	v_sub_u32_e32 v4, v219, v3
	s_nop 0
	v_cndmask_b32_e32 v105, v203, v105, vcc
	v_cmp_lt_i32_e32 vcc, -1, v4
	v_sub_u32_e32 v4, v220, v3
	s_nop 0
	v_cndmask_b32_e32 v106, v203, v106, vcc
	v_cmp_lt_i32_e32 vcc, -1, v4
	v_or_b32_e32 v4, s8, v223
	v_sub_u32_e32 v5, v209, v4
	v_cndmask_b32_e32 v107, v203, v107, vcc
	v_cmp_lt_i32_e32 vcc, -1, v5
	v_sub_u32_e32 v5, v4, v209
	s_nop 0
	v_cndmask_b32_e32 v108, v203, v108, vcc
	v_cmp_gt_i32_e32 vcc, 0, v5
	v_sub_u32_e32 v5, v219, v4
	s_nop 0
	v_cndmask_b32_e32 v109, v203, v109, vcc
	v_cmp_lt_i32_e32 vcc, -1, v5
	v_sub_u32_e32 v5, v220, v4
	s_nop 0
	v_cndmask_b32_e32 v110, v203, v110, vcc
	v_cmp_lt_i32_e32 vcc, -1, v5
	v_sub_u32_e32 v5, v224, v0
	s_nop 0
	v_cndmask_b32_e32 v111, v203, v111, vcc
	v_cmp_lt_i32_e32 vcc, -1, v5
	v_sub_u32_e32 v5, v225, v0
	s_nop 0
	v_cndmask_b32_e32 v80, v203, v80, vcc
	v_cmp_lt_i32_e32 vcc, -1, v5
	v_sub_u32_e32 v5, v226, v0
	v_sub_u32_e32 v0, v227, v0
	v_cndmask_b32_e32 v81, v203, v81, vcc
	v_cmp_lt_i32_e32 vcc, -1, v5
	s_nop 1
	v_cndmask_b32_e32 v82, v203, v82, vcc
	v_cmp_lt_i32_e32 vcc, -1, v0
	v_sub_u32_e32 v0, v224, v1
	s_nop 0
	v_cndmask_b32_e32 v83, v203, v83, vcc
	v_cmp_lt_i32_e32 vcc, -1, v0
	v_sub_u32_e32 v0, v225, v1
	s_nop 0
	v_cndmask_b32_e32 v84, v203, v84, vcc
	v_cmp_lt_i32_e32 vcc, -1, v0
	v_sub_u32_e32 v0, v226, v1
	s_nop 0
	v_cndmask_b32_e32 v85, v203, v85, vcc
	v_cmp_lt_i32_e32 vcc, -1, v0
	v_sub_u32_e32 v0, v227, v1
	s_nop 0
	v_cndmask_b32_e32 v86, v203, v86, vcc
	v_cmp_lt_i32_e32 vcc, -1, v0
	v_sub_u32_e32 v0, v224, v3
	s_nop 0
	v_cndmask_b32_e32 v87, v203, v87, vcc
	v_cmp_lt_i32_e32 vcc, -1, v0
	v_sub_u32_e32 v0, v225, v3
	s_nop 0
	v_cndmask_b32_e32 v88, v203, v88, vcc
	v_cmp_lt_i32_e32 vcc, -1, v0
	v_sub_u32_e32 v0, v226, v3
	s_nop 0
	v_cndmask_b32_e32 v89, v203, v89, vcc
	v_cmp_lt_i32_e32 vcc, -1, v0
	v_sub_u32_e32 v0, v227, v3
	s_nop 0
	v_cndmask_b32_e32 v90, v203, v90, vcc
	v_cmp_lt_i32_e32 vcc, -1, v0
	v_sub_u32_e32 v0, v224, v4
	s_nop 0
	v_cndmask_b32_e32 v91, v203, v91, vcc
	v_cmp_lt_i32_e32 vcc, -1, v0
	v_sub_u32_e32 v0, v225, v4
	s_nop 0
	v_cndmask_b32_e32 v92, v203, v92, vcc
	v_cmp_lt_i32_e32 vcc, -1, v0
	v_sub_u32_e32 v0, v226, v4
	s_nop 0
	v_cndmask_b32_e32 v93, v203, v93, vcc
	v_cmp_lt_i32_e32 vcc, -1, v0
	v_sub_u32_e32 v0, v227, v4
	s_nop 0
	v_cndmask_b32_e32 v94, v203, v94, vcc
	v_cmp_lt_i32_e32 vcc, -1, v0
	s_nop 1
	v_cndmask_b32_e32 v95, v203, v95, vcc

; #define LAS __attribute__((address_space(3)))
; DI unsigned f2bf(float f) { return pk2(f, 0.f) & 0xffffu; }
; #define MFMA32(a, b, c) __builtin_amdgcn_mfma_f32_32x32x16_bf16((a), (b), (c), 0, 0, 0)
; template <int BR, int NT, int DV> ...
;     ...
;     for (int ti = 0; ti < NT; ++ti) {
;         LAS unsigned char* kb = ti ? kbB : kbA; const int j = ti ? jB : jA;
; #pragma unroll
;         for (int i = 0; i < 16; ++i) { s[2 * ti][i] = 0.f; s[2 * ti + 1][i] = 0.f; }
; #pragma unroll
;         for (int ks = 0; ks < ((DV & 4) ? 0 : 4); ++ks) {
;             const bf16x8 a0 = *(const LAS bf16x8*)(kb + c.n * 144 + ks * 32 + c.h * 16);
;             const bf16x8 a1 = *(const LAS bf16x8*)(kb + (32 + c.n) * 144 + ks * 32 + c.h * 16);
;             s[2 * ti] = MFMA32(a0, c.qf[ks], s[2 * ti]); s[2 * ti + 1] = MFMA32(a1, c.qf[ks], s[2 * ti + 1]);
;         }
;         {
;             const int pos0 = (BR <= 1) ? (1024 * j + 31 - c.t) : (64 * j - c.t);
;             float tb = c.slope2 * (float)pos0;
;             if (BR == 2) { if (!m128_bit(c.sel_lo, c.sel_hi, j)) tb = -1e30f; }
;             const unsigned thi = f2bf(tb); const unsigned tlo = f2bf(tb - bf2f(thi));
;             u32x4 bw = (u32x4){(BR <= 1) ? c.slope16w : c.slopew, thi | (tlo << 16), 0u, 0u};
;             if (c.h) bw = (u32x4){0u, 0u, 0u, 0u};
;             const bf16x8 bb = __builtin_bit_cast(bf16x8, bw);
;             s[2 * ti] = MFMA32(c.akey[0], bb, s[2 * ti]); s[2 * ti + 1] = MFMA32(c.akey[1], bb, s[2 * ti + 1]);
;         }
;         bool bnd;
;         if (BR <= 1) bnd = (64 * j + 63 > 4 * qb - 2); else if (BR == 2) bnd = (j == qb); else bnd = (j == qb) || (j + 8 == qb);
;         if (bnd) {
;             asm volatile("" ::: "memory");
;             const int d0 = (BR <= 1) ? (c.t - 31 - 1024 * j) : (c.t - 64 * j);
; #pragma unroll
;             for (int kt = 0; kt < 2; ++kt)
; #pragma unroll
;                 for (int rr = 0; rr < 16; ++rr) {
;                     const int key = kt * 32 + (rr & 3) + 8 * (rr >> 2) + 4 * c.h;
;                     const int dist = (BR <= 1) ? (d0 - 16 * key) : (d0 - key);
;                     bool valid = dist >= 0;
;                     if (BR == 3) valid = valid && (dist < 512);
;                     s[2 * ti + kt][rr] = valid ? s[2 * ti + kt][rr] : -INFINITY;
;                 }
;         }
.LBB0_1083:
	v_add_u32_e32 v1, s19, v186
	v_add_u32_e32 v20, v1, v162
	ds_read_b128 v[4:7], v20 offset:4608
	ds_read_b128 v[8:11], v20
	ds_read_b128 v[22:25], v20 offset:32
	ds_read_b128 v[26:29], v20 offset:4640
	s_lshl_b32 s13, s18, 6
	v_sub_u32_e32 v1, s13, v209
	s_waitcnt lgkmcnt(2)
	v_mfma_f32_32x32x16_bf16 v[64:79], v[8:11], v[112:115], 0
	v_cvt_f32_i32_e32 v1, v1
	s_cmp_eq_u32 s18, s93
	s_cselect_b64 s[20:21], -1, 0
	s_add_i32 s18, s18, 8
	v_mul_f32_e32 v3, v210, v1
	v_cvt_pk_bf16_f32 v3, v3, 0
	v_and_b32_e32 v21, 0xffff, v3
	v_mfma_f32_32x32x16_bf16 v[4:19], v[4:7], v[112:115], 0
	v_lshlrev_b32_e32 v3, 16, v3
	v_fma_f32 v1, v210, v1, -v3
	v_cvt_pk_bf16_f32 v1, v1, 0
	v_lshl_or_b32 v1, v1, 16, v21
	v_cndmask_b32_e64 v1, 0, v1, s[6:7]
	v_mov_b32_e32 v3, v2
	s_cmp_eq_u32 s18, s93
	s_waitcnt lgkmcnt(1)
	v_mfma_f32_32x32x16_bf16 v[64:79], v[22:25], v[116:119], v[64:79]
	s_cselect_b64 s[22:23], -1, 0
	s_or_b64 s[20:21], s[20:21], s[22:23]
	s_andn2_b64 vcc, exec, s[20:21]
	s_waitcnt lgkmcnt(0)
	v_mfma_f32_32x32x16_bf16 v[4:19], v[26:29], v[116:119], v[4:19]
	ds_read_b128 v[22:25], v20 offset:64
	ds_read_b128 v[26:29], v20 offset:4672
	s_waitcnt lgkmcnt(1)
	v_mfma_f32_32x32x16_bf16 v[64:79], v[22:25], v[120:123], v[64:79]
	s_waitcnt lgkmcnt(0)
	v_mfma_f32_32x32x16_bf16 v[4:19], v[26:29], v[120:123], v[4:19]
	ds_read_b128 v[22:25], v20 offset:96
	ds_read_b128 v[26:29], v20 offset:4704
	s_waitcnt lgkmcnt(1)
	v_mfma_f32_32x32x16_bf16 v[64:79], v[22:25], v[124:127], v[64:79]
	s_waitcnt lgkmcnt(0)
	v_mfma_f32_32x32x16_bf16 v[4:19], v[26:29], v[124:127], v[4:19]
	v_mfma_f32_32x32x16_bf16 v[64:79], v[128:131], v[0:3], v[64:79]
	v_mfma_f32_32x32x16_bf16 v[4:19], v[132:135], v[0:3], v[4:19]
	s_cbranch_vccnz .LBB0_1085
	v_or_b32_e32 v1, s13, v154
	v_sub_u32_e32 v3, v209, v1
	v_cmp_gt_u32_e32 vcc, s41, v3
	v_sub_u32_e32 v3, v1, v209
	s_nop 5
	v_cndmask_b32_e32 v64, v203, v64, vcc
	v_cmp_lt_u32_e32 vcc, s96, v3
	v_sub_u32_e32 v3, v187, v1
	s_nop 0
	v_cndmask_b32_e32 v65, v203, v65, vcc
	v_cmp_gt_u32_e32 vcc, s41, v3
	v_sub_u32_e32 v3, v188, v1
	s_nop 0
	v_cndmask_b32_e32 v66, v203, v66, vcc
	v_cmp_gt_u32_e32 vcc, s41, v3
	v_or_b32_e32 v3, s13, v189
	v_sub_u32_e32 v21, v209, v3
	v_cndmask_b32_e32 v67, v203, v67, vcc
	v_cmp_gt_u32_e32 vcc, s41, v21
	v_sub_u32_e32 v21, v3, v209
	s_nop 0
	v_cndmask_b32_e32 v68, v203, v68, vcc
	v_cmp_lt_u32_e32 vcc, s96, v21
	v_sub_u32_e32 v21, v187, v3
	s_nop 0
	v_cndmask_b32_e32 v69, v203, v69, vcc
	v_cmp_gt_u32_e32 vcc, s41, v21
	v_sub_u32_e32 v21, v188, v3
	s_nop 0
	v_cndmask_b32_e32 v70, v203, v70, vcc
	v_cmp_gt_u32_e32 vcc, s41, v21
	v_or_b32_e32 v21, s13, v190
	v_sub_u32_e32 v22, v209, v21
	v_cndmask_b32_e32 v71, v203, v71, vcc
	v_cmp_gt_u32_e32 vcc, s41, v22
	v_sub_u32_e32 v22, v21, v209
	s_nop 0
	v_cndmask_b32_e32 v72, v203, v72, vcc
	v_cmp_lt_u32_e32 vcc, s96, v22
	v_sub_u32_e32 v22, v187, v21
	s_nop 0
	v_cndmask_b32_e32 v73, v203, v73, vcc
	v_cmp_gt_u32_e32 vcc, s41, v22
	v_sub_u32_e32 v22, v188, v21
	s_nop 0
	v_cndmask_b32_e32 v74, v203, v74, vcc
	v_cmp_gt_u32_e32 vcc, s41, v22
	v_or_b32_e32 v22, s13, v191
	v_sub_u32_e32 v23, v209, v22
	v_cndmask_b32_e32 v75, v203, v75, vcc
	v_cmp_gt_u32_e32 vcc, s41, v23
	v_sub_u32_e32 v23, v22, v209
	s_nop 0
	v_cndmask_b32_e32 v76, v203, v76, vcc
	v_cmp_lt_u32_e32 vcc, s96, v23
	v_sub_u32_e32 v23, v187, v22
	s_nop 0
	v_cndmask_b32_e32 v77, v203, v77, vcc
	v_cmp_gt_u32_e32 vcc, s41, v23
	v_sub_u32_e32 v23, v188, v22
	s_nop 0
	v_cndmask_b32_e32 v78, v203, v78, vcc
	v_cmp_gt_u32_e32 vcc, s41, v23
	v_sub_u32_e32 v23, v214, v1
	s_nop 0
	v_cndmask_b32_e32 v79, v203, v79, vcc
	v_cmp_gt_u32_e32 vcc, s41, v23
	v_sub_u32_e32 v23, v216, v1
	s_nop 0
	v_cndmask_b32_e32 v4, v203, v4, vcc
	v_cmp_gt_u32_e32 vcc, s41, v23
	v_sub_u32_e32 v23, v217, v1
	v_sub_u32_e32 v1, v218, v1
	v_cndmask_b32_e32 v5, v203, v5, vcc
	v_cmp_gt_u32_e32 vcc, s41, v23
	s_nop 1
	v_cndmask_b32_e32 v6, v203, v6, vcc
	v_cmp_gt_u32_e32 vcc, s41, v1
	v_sub_u32_e32 v1, v214, v3
	s_nop 0
	v_cndmask_b32_e32 v7, v203, v7, vcc
	v_cmp_gt_u32_e32 vcc, s41, v1
	v_sub_u32_e32 v1, v216, v3
	s_nop 0
	v_cndmask_b32_e32 v8, v203, v8, vcc
	v_cmp_gt_u32_e32 vcc, s41, v1
	v_sub_u32_e32 v1, v217, v3
	s_nop 0
	v_cndmask_b32_e32 v9, v203, v9, vcc
	v_cmp_gt_u32_e32 vcc, s41, v1
	v_sub_u32_e32 v1, v218, v3
	s_nop 0
	v_cndmask_b32_e32 v10, v203, v10, vcc
	v_cmp_gt_u32_e32 vcc, s41, v1
	v_sub_u32_e32 v1, v214, v21
	s_nop 0
	v_cndmask_b32_e32 v11, v203, v11, vcc
	v_cmp_gt_u32_e32 vcc, s41, v1
	v_sub_u32_e32 v1, v216, v21
	s_nop 0
	v_cndmask_b32_e32 v12, v203, v12, vcc
	v_cmp_gt_u32_e32 vcc, s41, v1
	v_sub_u32_e32 v1, v217, v21
	s_nop 0
	v_cndmask_b32_e32 v13, v203, v13, vcc
	v_cmp_gt_u32_e32 vcc, s41, v1
	v_sub_u32_e32 v1, v218, v21
	s_nop 0
	v_cndmask_b32_e32 v14, v203, v14, vcc
	v_cmp_gt_u32_e32 vcc, s41, v1
	v_sub_u32_e32 v1, v214, v22
	s_nop 0
	v_cndmask_b32_e32 v15, v203, v15, vcc
	v_cmp_gt_u32_e32 vcc, s41, v1
	v_sub_u32_e32 v1, v216, v22
	s_nop 0
	v_cndmask_b32_e32 v16, v203, v16, vcc
	v_cmp_gt_u32_e32 vcc, s41, v1
	v_sub_u32_e32 v1, v217, v22
	s_nop 0
	v_cndmask_b32_e32 v17, v203, v17, vcc
	v_cmp_gt_u32_e32 vcc, s41, v1
	v_sub_u32_e32 v1, v218, v22
	s_nop 0
	v_cndmask_b32_e32 v18, v203, v18, vcc
	v_cmp_gt_u32_e32 vcc, s41, v1
	s_nop 1
	v_cndmask_b32_e32 v19, v203, v19, vcc
; #define LAS __attribute__((address_space(3)))
; DI unsigned f2bf(float f) { return pk2(f, 0.f) & 0xffffu; }
; #define MFMA32(a, b, c) __builtin_amdgcn_mfma_f32_32x32x16_bf16((a), (b), (c), 0, 0, 0)
; template <int BR, int NT, int DV> ...
;     ...
;     for (int ti = 0; ti < NT; ++ti) {
;         LAS unsigned char* kb = ti ? kbB : kbA; const int j = ti ? jB : jA;
; #pragma unroll
;         for (int i = 0; i < 16; ++i) { s[2 * ti][i] = 0.f; s[2 * ti + 1][i] = 0.f; }
; #pragma unroll
;         for (int ks = 0; ks < ((DV & 4) ? 0 : 4); ++ks) {
;             const bf16x8 a0 = *(const LAS bf16x8*)(kb + c.n * 144 + ks * 32 + c.h * 16);
;             const bf16x8 a1 = *(const LAS bf16x8*)(kb + (32 + c.n) * 144 + ks * 32 + c.h * 16);
;             s[2 * ti] = MFMA32(a0, c.qf[ks], s[2 * ti]); s[2 * ti + 1] = MFMA32(a1, c.qf[ks], s[2 * ti + 1]);
;         }
;         {
;             const int pos0 = (BR <= 1) ? (1024 * j + 31 - c.t) : (64 * j - c.t);
;             float tb = c.slope2 * (float)pos0;
;             if (BR == 2) { if (!m128_bit(c.sel_lo, c.sel_hi, j)) tb = -1e30f; }
;             const unsigned thi = f2bf(tb); const unsigned tlo = f2bf(tb - bf2f(thi));
;             u32x4 bw = (u32x4){(BR <= 1) ? c.slope16w : c.slopew, thi | (tlo << 16), 0u, 0u};
;             if (c.h) bw = (u32x4){0u, 0u, 0u, 0u};
;             const bf16x8 bb = __builtin_bit_cast(bf16x8, bw);
;             s[2 * ti] = MFMA32(c.akey[0], bb, s[2 * ti]); s[2 * ti + 1] = MFMA32(c.akey[1], bb, s[2 * ti + 1]);
;         }
;         bool bnd;
;         if (BR <= 1) bnd = (64 * j + 63 > 4 * qb - 2); else if (BR == 2) bnd = (j == qb); else bnd = (j == qb) || (j + 8 == qb);
;         if (bnd) {
;             asm volatile("" ::: "memory");
;             const int d0 = (BR <= 1) ? (c.t - 31 - 1024 * j) : (c.t - 64 * j);
; #pragma unroll
;             for (int kt = 0; kt < 2; ++kt)
; #pragma unroll
;                 for (int rr = 0; rr < 16; ++rr) {
;                     const int key = kt * 32 + (rr & 3) + 8 * (rr >> 2) + 4 * c.h;
;                     const int dist = (BR <= 1) ? (d0 - 16 * key) : (d0 - key);
;                     bool valid = dist >= 0;
;                     if (BR == 3) valid = valid && (dist < 512);
;                     s[2 * ti + kt][rr] = valid ? s[2 * ti + kt][rr] : -INFINITY;
;                 }
;         }
.LBB0_1085:
	ds_read_b128 v[22:25], v20 offset:13824
	ds_read_b128 v[26:29], v20 offset:9216
	ds_read_b128 v[166:169], v20 offset:9248
	s_lshl_b32 s13, s16, 6
	v_sub_u32_e32 v1, s13, v209
	s_waitcnt lgkmcnt(2)
	v_mfma_f32_32x32x16_bf16 v[80:95], v[22:25], v[112:115], 0
	ds_read_b128 v[22:25], v20 offset:13856
	v_cvt_f32_i32_e32 v1, v1
	s_cmp_eq_u32 s16, s93
	s_cselect_b64 s[20:21], -1, 0
	s_add_i32 s16, s16, 8
	v_mul_f32_e32 v3, v210, v1
	v_cvt_pk_bf16_f32 v3, v3, 0
	s_waitcnt lgkmcnt(2)
	v_mfma_f32_32x32x16_bf16 v[96:111], v[26:29], v[112:115], 0
	s_cmp_eq_u32 s16, s93
	s_cselect_b64 s[22:23], -1, 0
	s_or_b64 s[20:21], s[20:21], s[22:23]
	s_andn2_b64 vcc, exec, s[20:21]
	s_waitcnt lgkmcnt(1)
	v_mfma_f32_32x32x16_bf16 v[96:111], v[166:169], v[116:119], v[96:111]
	s_waitcnt lgkmcnt(0)
	v_mfma_f32_32x32x16_bf16 v[80:95], v[22:25], v[116:119], v[80:95]
	ds_read_b128 v[22:25], v20 offset:9280
	ds_read_b128 v[26:29], v20 offset:13888
	s_waitcnt lgkmcnt(1)
	v_mfma_f32_32x32x16_bf16 v[96:111], v[22:25], v[120:123], v[96:111]
	s_waitcnt lgkmcnt(0)
	v_mfma_f32_32x32x16_bf16 v[80:95], v[26:29], v[120:123], v[80:95]
	ds_read_b128 v[22:25], v20 offset:9312
	ds_read_b128 v[26:29], v20 offset:13920
	v_and_b32_e32 v20, 0xffff, v3
	v_lshlrev_b32_e32 v3, 16, v3
	v_fma_f32 v1, v210, v1, -v3
	v_cvt_pk_bf16_f32 v1, v1, 0
	v_lshl_or_b32 v1, v1, 16, v20
	v_cndmask_b32_e64 v1, 0, v1, s[6:7]
	s_waitcnt lgkmcnt(1)
	v_mfma_f32_32x32x16_bf16 v[96:111], v[22:25], v[124:127], v[96:111]
	v_mov_b32_e32 v3, v2
	s_waitcnt lgkmcnt(0)
	v_mfma_f32_32x32x16_bf16 v[80:95], v[26:29], v[124:127], v[80:95]
	v_mfma_f32_32x32x16_bf16 v[96:111], v[128:131], v[0:3], v[96:111]
	v_mfma_f32_32x32x16_bf16 v[80:95], v[132:135], v[0:3], v[80:95]
	s_cbranch_vccnz .LBB0_1087
	v_or_b32_e32 v0, s13, v154
	v_sub_u32_e32 v1, v209, v0
	v_cmp_gt_u32_e32 vcc, s41, v1
	v_sub_u32_e32 v1, v0, v209
	s_nop 5
	v_cndmask_b32_e32 v96, v203, v96, vcc
	v_cmp_lt_u32_e32 vcc, s96, v1
	v_sub_u32_e32 v1, v187, v0
	s_nop 0
	v_cndmask_b32_e32 v97, v203, v97, vcc
	v_cmp_gt_u32_e32 vcc, s41, v1
	v_sub_u32_e32 v1, v188, v0
	s_nop 0
	v_cndmask_b32_e32 v98, v203, v98, vcc
	v_cmp_gt_u32_e32 vcc, s41, v1
	v_or_b32_e32 v1, s13, v189
	v_sub_u32_e32 v3, v209, v1
	v_cndmask_b32_e32 v99, v203, v99, vcc
	v_cmp_gt_u32_e32 vcc, s41, v3
	v_sub_u32_e32 v3, v1, v209
	s_nop 0
	v_cndmask_b32_e32 v100, v203, v100, vcc
	v_cmp_lt_u32_e32 vcc, s96, v3
	v_sub_u32_e32 v3, v187, v1
	s_nop 0
	v_cndmask_b32_e32 v101, v203, v101, vcc
	v_cmp_gt_u32_e32 vcc, s41, v3
	v_sub_u32_e32 v3, v188, v1
	s_nop 0
	v_cndmask_b32_e32 v102, v203, v102, vcc
	v_cmp_gt_u32_e32 vcc, s41, v3
	v_or_b32_e32 v3, s13, v190
	v_sub_u32_e32 v20, v209, v3
	v_cndmask_b32_e32 v103, v203, v103, vcc
	v_cmp_gt_u32_e32 vcc, s41, v20
	v_sub_u32_e32 v20, v3, v209
	s_nop 0
	v_cndmask_b32_e32 v104, v203, v104, vcc
	v_cmp_lt_u32_e32 vcc, s96, v20
	v_sub_u32_e32 v20, v187, v3
	s_nop 0
	v_cndmask_b32_e32 v105, v203, v105, vcc
	v_cmp_gt_u32_e32 vcc, s41, v20
	v_sub_u32_e32 v20, v188, v3
	s_nop 0
	v_cndmask_b32_e32 v106, v203, v106, vcc
	v_cmp_gt_u32_e32 vcc, s41, v20
	v_or_b32_e32 v20, s13, v191
	v_sub_u32_e32 v21, v209, v20
	v_cndmask_b32_e32 v107, v203, v107, vcc
	v_cmp_gt_u32_e32 vcc, s41, v21
	v_sub_u32_e32 v21, v20, v209
	s_nop 0
	v_cndmask_b32_e32 v108, v203, v108, vcc
	v_cmp_lt_u32_e32 vcc, s96, v21
	v_sub_u32_e32 v21, v187, v20
	s_nop 0
	v_cndmask_b32_e32 v109, v203, v109, vcc
	v_cmp_gt_u32_e32 vcc, s41, v21
	v_sub_u32_e32 v21, v188, v20
	s_nop 0
	v_cndmask_b32_e32 v110, v203, v110, vcc
	v_cmp_gt_u32_e32 vcc, s41, v21
	v_sub_u32_e32 v21, v214, v0
	s_nop 0
	v_cndmask_b32_e32 v111, v203, v111, vcc
	v_cmp_gt_u32_e32 vcc, s41, v21
	v_sub_u32_e32 v21, v216, v0
	s_nop 0
	v_cndmask_b32_e32 v80, v203, v80, vcc
	v_cmp_gt_u32_e32 vcc, s41, v21
	v_sub_u32_e32 v21, v217, v0
	v_sub_u32_e32 v0, v218, v0
	v_cndmask_b32_e32 v81, v203, v81, vcc
	v_cmp_gt_u32_e32 vcc, s41, v21
	s_nop 1
	v_cndmask_b32_e32 v82, v203, v82, vcc
	v_cmp_gt_u32_e32 vcc, s41, v0
	v_sub_u32_e32 v0, v214, v1
	s_nop 0
	v_cndmask_b32_e32 v83, v203, v83, vcc
	v_cmp_gt_u32_e32 vcc, s41, v0
	v_sub_u32_e32 v0, v216, v1
	s_nop 0
	v_cndmask_b32_e32 v84, v203, v84, vcc
	v_cmp_gt_u32_e32 vcc, s41, v0
	v_sub_u32_e32 v0, v217, v1
	s_nop 0
	v_cndmask_b32_e32 v85, v203, v85, vcc
	v_cmp_gt_u32_e32 vcc, s41, v0
	v_sub_u32_e32 v0, v218, v1
	s_nop 0
	v_cndmask_b32_e32 v86, v203, v86, vcc
	v_cmp_gt_u32_e32 vcc, s41, v0
	v_sub_u32_e32 v0, v214, v3
	s_nop 0
	v_cndmask_b32_e32 v87, v203, v87, vcc
	v_cmp_gt_u32_e32 vcc, s41, v0
	v_sub_u32_e32 v0, v216, v3
	s_nop 0
	v_cndmask_b32_e32 v88, v203, v88, vcc
	v_cmp_gt_u32_e32 vcc, s41, v0
	v_sub_u32_e32 v0, v217, v3
	s_nop 0
	v_cndmask_b32_e32 v89, v203, v89, vcc
	v_cmp_gt_u32_e32 vcc, s41, v0
	v_sub_u32_e32 v0, v218, v3
	s_nop 0
	v_cndmask_b32_e32 v90, v203, v90, vcc
	v_cmp_gt_u32_e32 vcc, s41, v0
	v_sub_u32_e32 v0, v214, v20
	s_nop 0
	v_cndmask_b32_e32 v91, v203, v91, vcc
	v_cmp_gt_u32_e32 vcc, s41, v0
	v_sub_u32_e32 v0, v216, v20
	s_nop 0
	v_cndmask_b32_e32 v92, v203, v92, vcc
	v_cmp_gt_u32_e32 vcc, s41, v0
	v_sub_u32_e32 v0, v217, v20
	s_nop 0
	v_cndmask_b32_e32 v93, v203, v93, vcc
	v_cmp_gt_u32_e32 vcc, s41, v0
	v_sub_u32_e32 v0, v218, v20
	s_nop 0
	v_cndmask_b32_e32 v94, v203, v94, vcc
	v_cmp_gt_u32_e32 vcc, s41, v0
	s_nop 1
	v_cndmask_b32_e32 v95, v203, v95, vcc

; DI float sigmoidf_(float x) { return __builtin_amdgcn_rcpf(1.f + __builtin_amdgcn_exp2f(fminf(-x * LOG2E, 126.f))); }
;     DI void operator()(const f32x4 (&acc)[2][2][4][2], const Unit& u, int wr, int wc, int fr, int fq) const {
;         f32x4 b0[2], b1[2];
; #pragma unroll
;         for (int bj = 0; bj < 2; ++bj) { const int col0 = u.pn * 256 + bj * 128 + wc * 32 + 8 * fq; b0[bj] = *(const f32x4*)(bias + col0); b1[bj] = *(const f32x4*)(bias + col0 + 4); }
; #pragma unroll
;         for (int ai = 0; ai < 2; ++ai) {
;             u32x4 pw[4][2], xw[4][2];
; #pragma unroll
;             for (int m = 0; m < 4; ++m)
; #pragma unroll
;                 for (int bj = 0; bj < 2; ++bj) {
;                     const size_t off = (size_t)(u.pm * 256 + ai * 128 + wr * 64 + m * 16 + fr) * DM + u.pn * 256 + bj * 128 + wc * 32 + 8 * fq;
;                     pw[m][bj] = *(const u32x4*)(pp + off); xw[m][bj] = *(const u32x4*)(xb + off);
;                 }
; #pragma unroll
;             for (int m = 0; m < 4; ++m)
; #pragma unroll
;                 for (int bj = 0; bj < 2; ++bj) {
;                     const size_t off = (size_t)(u.pm * 256 + ai * 128 + wr * 64 + m * 16 + fr) * DM + u.pn * 256 + bj * 128 + wc * 32 + 8 * fq;
;                     const u32x4 p = pw[m][bj], x = xw[m][bj];
;                     const f32x4 a0 = acc[ai][bj][m][0] + b0[bj], a1 = acc[ai][bj][m][1] + b1[bj];
;                     f32x4 x0, x1;
;                     x0[0] = bflo(x.x) + sigmoidf_(a0[0]) * bflo(p.x); x0[1] = bfhi(x.x) + sigmoidf_(a0[1]) * bfhi(p.x); x0[2] = bflo(x.y) + sigmoidf_(a0[2]) * bflo(p.y); x0[3] = bfhi(x.y) + sigmoidf_(a0[3]) * bfhi(p.y);
;                     x1[0] = bflo(x.z) + sigmoidf_(a1[0]) * bflo(p.z); x1[1] = bfhi(x.z) + sigmoidf_(a1[1]) * bfhi(p.z); x1[2] = bflo(x.w) + sigmoidf_(a1[2]) * bflo(p.w); x1[3] = bfhi(x.w) + sigmoidf_(a1[3]) * bfhi(p.w);
;                     *(f32x4*)(out + off) = x0; *(f32x4*)(out + off + 4) = x1;
.LBB0_1662:
	v_mbcnt_lo_u32_b32 v246, -1, 0
	v_mbcnt_hi_u32_b32 v246, -1, v246
	v_and_b32_e32 v246, 48, v246
	v_sub_u32_e32 v246, 0, v246
	v_ashrrev_i32_e32 v247, 31, v246
	s_lshl_b32 s13, s39, 8
	v_or_b32_e32 v210, s13, v200
	v_lshl_add_u32 v212, s22, 8, v201
	v_ashrrev_i32_e32 v211, 31, v210
	s_ashr_i32 s13, s13, 31
	v_ashrrev_i32_e32 v213, 31, v212
	v_lshl_add_u64 v[68:69], v[210:211], 2, s[8:9]
	v_lshlrev_b64 v[64:65], 10, v[212:213]
	v_mov_b32_e32 v211, s13
	global_load_dwordx4 v[76:79], v[68:69], off
	global_load_dwordx4 v[72:75], v[68:69], off offset:16
	v_lshl_add_u64 v[240:241], v[64:65], 0, v[210:211]
	v_lshlrev_b64 v[136:137], 1, v[240:241]
	v_readlane_b32 s24, v254, 18
	v_lshl_add_u64 v[64:65], s[16:17], 0, v[136:137]
	v_readlane_b32 s25, v254, 19
	global_load_dwordx4 v[224:227], v[64:65], off
	v_or_b32_e32 v66, 32, v212
	v_lshl_add_u64 v[64:65], s[24:25], 0, v[136:137]
	global_load_dwordx4 v[228:231], v[64:65], off
	v_or_b32_e32 v64, 16, v212
	v_or_b32_e32 v70, 48, v212
	v_ashrrev_i32_e32 v65, 31, v64
	v_ashrrev_i32_e32 v67, 31, v66
	v_ashrrev_i32_e32 v71, 31, v70
	v_lshlrev_b64 v[138:139], 10, v[64:65]
	v_lshlrev_b64 v[140:141], 10, v[66:67]
	v_lshlrev_b64 v[142:143], 10, v[70:71]
	global_load_dwordx4 v[64:67], v[68:69], off offset:528
	s_nop 0
	global_load_dwordx4 v[68:71], v[68:69], off offset:512
	v_lshl_add_u64 v[218:219], v[138:139], 0, v[210:211]
	v_lshl_add_u64 v[216:217], v[140:141], 0, v[210:211]
	v_lshl_add_u64 v[214:215], v[142:143], 0, v[210:211]
	v_lshlrev_b64 v[138:139], 1, v[218:219]
	v_lshlrev_b64 v[140:141], 1, v[216:217]
	v_lshlrev_b64 v[142:143], 1, v[214:215]
	v_or_b32_e32 v136, 0x100, v136
	v_lshl_add_u64 v[152:153], s[24:25], 0, v[138:139]
	v_lshl_add_u64 v[154:155], s[16:17], 0, v[138:139]
	v_or_b32_e32 v138, 0x100, v138
	v_lshl_add_u64 v[156:157], s[24:25], 0, v[140:141]
	v_lshl_add_u64 v[158:159], s[16:17], 0, v[140:141]
	v_or_b32_e32 v140, 0x100, v140
	v_lshl_add_u64 v[160:161], s[24:25], 0, v[142:143]
	v_lshl_add_u64 v[162:163], s[16:17], 0, v[142:143]
	v_or_b32_e32 v142, 0x100, v142
	v_lshl_add_u64 v[164:165], s[24:25], 0, v[136:137]
	v_lshl_add_u64 v[136:137], s[16:17], 0, v[136:137]
	v_lshl_add_u64 v[166:167], s[24:25], 0, v[138:139]
	v_lshl_add_u64 v[138:139], s[16:17], 0, v[138:139]
	v_lshl_add_u64 v[242:243], s[24:25], 0, v[140:141]
	v_lshl_add_u64 v[140:141], s[16:17], 0, v[140:141]
	v_lshl_add_u64 v[244:245], s[24:25], 0, v[142:143]
	v_lshl_add_u64 v[142:143], s[16:17], 0, v[142:143]
	global_load_dwordx4 v[184:187], v[152:153], off
	global_load_dwordx4 v[188:191], v[154:155], off
	global_load_dwordx4 v[168:171], v[156:157], off
	global_load_dwordx4 v[172:175], v[158:159], off
	s_nop 0
	global_load_dwordx4 v[152:155], v[160:161], off
	global_load_dwordx4 v[156:159], v[162:163], off
	global_load_dwordx4 v[232:235], v[164:165], off
	global_load_dwordx4 v[236:239], v[136:137], off
	global_load_dwordx4 v[176:179], v[166:167], off
	global_load_dwordx4 v[180:183], v[138:139], off
	s_nop 0
	global_load_dwordx4 v[160:163], v[242:243], off
	global_load_dwordx4 v[164:167], v[140:141], off
	global_load_dwordx4 v[136:139], v[244:245], off
	s_nop 0
	global_load_dwordx4 v[140:143], v[142:143], off
	s_andn2_b64 vcc, exec, s[4:5]
	s_mov_b64 s[4:5], -1
	s_waitcnt vmcnt(0)
	v_pk_add_f32 v[148:149], v[148:149], v[76:77]
	v_pk_add_f32 v[150:151], v[150:151], v[78:79]
	v_pk_add_f32 v[242:243], v[146:147], v[74:75]
	v_pk_add_f32 v[146:147], v[144:145], v[72:73]
	v_mul_f32_e32 v144, 0xbfb8aa3b, v148
	v_mul_f32_e32 v145, 0xbfb8aa3b, v149
	v_mul_f32_e32 v148, 0xbfb8aa3b, v150
	v_min_f32_e32 v144, 0x42fc0000, v144
	v_min_f32_e32 v145, 0x42fc0000, v145
	v_mul_f32_e32 v149, 0xbfb8aa3b, v151
	v_min_f32_e32 v150, 0x42fc0000, v148
	v_exp_f32_e32 v213, v144
	v_exp_f32_e32 v244, v145
	v_min_f32_e32 v151, 0x42fc0000, v149
	v_lshlrev_b32_e32 v144, 16, v224
	v_and_b32_e32 v145, 0xffff0000, v224
	v_exp_f32_e32 v224, v150
	v_lshlrev_b32_e32 v148, 16, v228
	v_and_b32_e32 v149, 0xffff0000, v228
	v_exp_f32_e32 v228, v151
	v_lshlrev_b32_e32 v150, 16, v225
	v_and_b32_e32 v151, 0xffff0000, v225
	v_add_f32_e32 v213, 1.0, v213
	v_add_f32_e32 v225, 1.0, v244
	v_add_f32_e32 v244, 1.0, v224
	v_rcp_f32_e32 v224, v213
	v_rcp_f32_e32 v225, v225
	v_mul_f32_e32 v146, 0xbfb8aa3b, v146
	v_add_f32_e32 v213, 1.0, v228
	v_min_f32_e32 v146, 0x42fc0000, v146
	v_rcp_f32_e32 v245, v213
	v_exp_f32_e32 v213, v146
	v_mul_f32_e32 v146, 0xbfb8aa3b, v147
	v_rcp_f32_e32 v244, v244
	v_min_f32_e32 v146, 0x42fc0000, v146
	v_pk_fma_f32 v[144:145], v[224:225], v[148:149], v[144:145]
	v_exp_f32_e32 v224, v146
	v_lshlrev_b32_e32 v148, 16, v229
	v_and_b32_e32 v149, 0xffff0000, v229
	v_pk_fma_f32 v[146:147], v[244:245], v[148:149], v[150:151]
	v_add_f32_e32 v148, 1.0, v213
	v_lshlrev_b32_e32 v150, 16, v226
	v_and_b32_e32 v151, 0xffff0000, v226
	v_mul_f32_e32 v213, 0xbfb8aa3b, v242
	v_mul_f32_e32 v226, 0xbfb8aa3b, v243
	v_add_f32_e32 v149, 1.0, v224
	v_min_f32_e32 v213, 0x42fc0000, v213
	v_min_f32_e32 v226, 0x42fc0000, v226
	v_rcp_f32_e32 v148, v148
	v_rcp_f32_e32 v149, v149
	v_exp_f32_e32 v213, v213
	v_exp_f32_e32 v226, v226
	v_lshlrev_b32_e32 v224, 16, v230
	v_and_b32_e32 v225, 0xffff0000, v230
	v_pk_fma_f32 v[148:149], v[148:149], v[224:225], v[150:151]
	v_add_f32_e32 v150, 1.0, v213
	v_add_f32_e32 v151, 1.0, v226
	v_rcp_f32_e32 v150, v150
	v_rcp_f32_e32 v151, v151
	v_lshlrev_b32_e32 v224, 16, v227
	v_and_b32_e32 v225, 0xffff0000, v227
	v_lshlrev_b32_e32 v226, 16, v231
	v_and_b32_e32 v227, 0xffff0000, v231
	v_pk_fma_f32 v[150:151], v[150:151], v[226:227], v[224:225]
	v_lshl_add_u64 v[224:225], v[240:241], 2, s[10:11]
	v_lshl_add_u64 v[224:225], v[224:225], 0, v[246:247]
; DI float sigmoidf_(float x) { return __builtin_amdgcn_rcpf(1.f + __builtin_amdgcn_exp2f(fminf(-x * LOG2E, 126.f))); }
;     DI void operator()(const f32x4 (&acc)[2][2][4][2], const Unit& u, int wr, int wc, int fr, int fq) const {
;     ...
; #pragma unroll
;             for (int m = 0; m < 4; ++m)
; #pragma unroll
;                 for (int bj = 0; bj < 2; ++bj) {
;                     const size_t off = (size_t)(u.pm * 256 + ai * 128 + wr * 64 + m * 16 + fr) * DM + u.pn * 256 + bj * 128 + wc * 32 + 8 * fq;
;                     const u32x4 p = pw[m][bj], x = xw[m][bj];
;                     const f32x4 a0 = acc[ai][bj][m][0] + b0[bj], a1 = acc[ai][bj][m][1] + b1[bj];
;                     f32x4 x0, x1;
;                     x0[0] = bflo(x.x) + sigmoidf_(a0[0]) * bflo(p.x); x0[1] = bfhi(x.x) + sigmoidf_(a0[1]) * bfhi(p.x); x0[2] = bflo(x.y) + sigmoidf_(a0[2]) * bflo(p.y); x0[3] = bfhi(x.y) + sigmoidf_(a0[3]) * bfhi(p.y);
;                     x1[0] = bflo(x.z) + sigmoidf_(a1[0]) * bflo(p.z); x1[1] = bfhi(x.z) + sigmoidf_(a1[1]) * bfhi(p.z); x1[2] = bflo(x.w) + sigmoidf_(a1[2]) * bflo(p.w); x1[3] = bfhi(x.w) + sigmoidf_(a1[3]) * bfhi(p.w);
;                     *(f32x4*)(out + off) = x0; *(f32x4*)(out + off + 4) = x1;
	v_pk_add_f32 v[132:133], v[132:133], v[68:69]
	s_nop 1
	v_permlane16_swap_b32 v144, v148
	v_permlane16_swap_b32 v145, v149
	v_permlane16_swap_b32 v146, v150
	v_permlane16_swap_b32 v147, v151
	v_permlane32_swap_b32 v144, v148
	v_permlane32_swap_b32 v145, v149
	v_permlane32_swap_b32 v146, v150
	v_permlane32_swap_b32 v147, v151
	global_store_dwordx4 v[224:225], v[144:147], off
	global_store_dwordx4 v[224:225], v[148:151], off offset:64
	v_pk_add_f32 v[134:135], v[134:135], v[70:71]
	v_pk_add_f32 v[144:145], v[130:131], v[66:67]
	v_mul_f32_e32 v130, 0xbfb8aa3b, v132
	v_min_f32_e32 v130, 0x42fc0000, v130
	v_exp_f32_e32 v132, v130
	v_mul_f32_e32 v130, 0xbfb8aa3b, v133
	v_min_f32_e32 v130, 0x42fc0000, v130
	v_exp_f32_e32 v133, v130
	v_mul_f32_e32 v134, 0xbfb8aa3b, v134
	v_mul_f32_e32 v135, 0xbfb8aa3b, v135
	v_pk_add_f32 v[130:131], v[128:129], v[64:65]
	v_add_f32_e32 v128, 1.0, v132
	v_add_f32_e32 v129, 1.0, v133
	v_min_f32_e32 v134, 0x42fc0000, v134
	v_min_f32_e32 v135, 0x42fc0000, v135
	v_rcp_f32_e32 v128, v128
	v_rcp_f32_e32 v129, v129
	v_exp_f32_e32 v134, v134
	v_exp_f32_e32 v135, v135
	v_mul_f32_e32 v130, 0xbfb8aa3b, v130
	v_min_f32_e32 v130, 0x42fc0000, v130
	v_lshlrev_b32_e32 v132, 16, v236
	v_and_b32_e32 v133, 0xffff0000, v236
	v_lshlrev_b32_e32 v146, 16, v232
	v_and_b32_e32 v147, 0xffff0000, v232
	v_exp_f32_e32 v148, v130
	v_mul_f32_e32 v130, 0xbfb8aa3b, v131
	v_pk_fma_f32 v[128:129], v[128:129], v[146:147], v[132:133]
	v_add_f32_e32 v132, 1.0, v134
	v_add_f32_e32 v133, 1.0, v135
	v_min_f32_e32 v130, 0x42fc0000, v130
	v_rcp_f32_e32 v132, v132
	v_rcp_f32_e32 v133, v133
	v_exp_f32_e32 v149, v130
	v_lshlrev_b32_e32 v134, 16, v237
	v_and_b32_e32 v135, 0xffff0000, v237
	v_lshlrev_b32_e32 v146, 16, v233
	v_and_b32_e32 v147, 0xffff0000, v233
	v_mul_f32_e32 v144, 0xbfb8aa3b, v144
	v_mul_f32_e32 v145, 0xbfb8aa3b, v145
	v_pk_fma_f32 v[130:131], v[132:133], v[146:147], v[134:135]
	v_add_f32_e32 v132, 1.0, v148
	v_add_f32_e32 v133, 1.0, v149
	v_min_f32_e32 v144, 0x42fc0000, v144
	v_min_f32_e32 v145, 0x42fc0000, v145
	v_rcp_f32_e32 v132, v132
	v_rcp_f32_e32 v133, v133
	v_exp_f32_e32 v144, v144
	v_exp_f32_e32 v145, v145
	v_lshlrev_b32_e32 v134, 16, v238
	v_and_b32_e32 v135, 0xffff0000, v238
	v_lshlrev_b32_e32 v146, 16, v234
	v_and_b32_e32 v147, 0xffff0000, v234
	v_pk_fma_f32 v[132:133], v[132:133], v[146:147], v[134:135]
	v_add_f32_e32 v134, 1.0, v144
	v_add_f32_e32 v135, 1.0, v145
	v_rcp_f32_e32 v134, v134
	v_rcp_f32_e32 v135, v135
	v_lshlrev_b32_e32 v144, 16, v239
	v_and_b32_e32 v145, 0xffff0000, v239
	v_lshlrev_b32_e32 v146, 16, v235
	v_and_b32_e32 v147, 0xffff0000, v235
	v_pk_add_f32 v[124:125], v[124:125], v[76:77]
	v_pk_fma_f32 v[134:135], v[134:135], v[146:147], v[144:145]
	s_nop 1
	v_permlane16_swap_b32 v128, v132
	v_permlane16_swap_b32 v129, v133
	v_permlane16_swap_b32 v130, v134
	v_permlane16_swap_b32 v131, v135
	v_permlane32_swap_b32 v128, v132
	v_permlane32_swap_b32 v129, v133
	v_permlane32_swap_b32 v130, v134
	v_permlane32_swap_b32 v131, v135
	global_store_dwordx4 v[224:225], v[128:131], off offset:512
	global_store_dwordx4 v[224:225], v[132:135], off offset:576
	v_pk_add_f32 v[126:127], v[126:127], v[78:79]
	v_pk_add_f32 v[128:129], v[122:123], v[74:75]
	v_mul_f32_e32 v122, 0xbfb8aa3b, v124
	v_min_f32_e32 v122, 0x42fc0000, v122
	v_exp_f32_e32 v124, v122
	v_mul_f32_e32 v122, 0xbfb8aa3b, v125
	v_min_f32_e32 v122, 0x42fc0000, v122
	v_exp_f32_e32 v125, v122
	v_mul_f32_e32 v126, 0xbfb8aa3b, v126
	v_mul_f32_e32 v127, 0xbfb8aa3b, v127
	v_pk_add_f32 v[122:123], v[120:121], v[72:73]
	v_add_f32_e32 v120, 1.0, v124
	v_add_f32_e32 v121, 1.0, v125
	v_min_f32_e32 v126, 0x42fc0000, v126
	v_min_f32_e32 v127, 0x42fc0000, v127
	v_rcp_f32_e32 v120, v120
	v_rcp_f32_e32 v121, v121
	v_exp_f32_e32 v126, v126
	v_exp_f32_e32 v127, v127
	v_mul_f32_e32 v122, 0xbfb8aa3b, v122
	v_min_f32_e32 v122, 0x42fc0000, v122
	v_lshlrev_b32_e32 v124, 16, v188
	v_and_b32_e32 v125, 0xffff0000, v188
	v_lshlrev_b32_e32 v130, 16, v184
	v_and_b32_e32 v131, 0xffff0000, v184
	v_exp_f32_e32 v132, v122
	v_mul_f32_e32 v122, 0xbfb8aa3b, v123
	v_pk_fma_f32 v[120:121], v[120:121], v[130:131], v[124:125]
	v_add_f32_e32 v124, 1.0, v126
	v_add_f32_e32 v125, 1.0, v127
	v_min_f32_e32 v122, 0x42fc0000, v122
	v_rcp_f32_e32 v124, v124
	v_rcp_f32_e32 v125, v125
	v_exp_f32_e32 v133, v122
	v_lshlrev_b32_e32 v126, 16, v189
	v_and_b32_e32 v127, 0xffff0000, v189
	v_lshlrev_b32_e32 v130, 16, v185
	v_and_b32_e32 v131, 0xffff0000, v185
	v_mul_f32_e32 v128, 0xbfb8aa3b, v128
	v_mul_f32_e32 v129, 0xbfb8aa3b, v129
	v_pk_fma_f32 v[122:123], v[124:125], v[130:131], v[126:127]
	v_add_f32_e32 v124, 1.0, v132
	v_add_f32_e32 v125, 1.0, v133
	v_min_f32_e32 v128, 0x42fc0000, v128
	v_min_f32_e32 v129, 0x42fc0000, v129
	v_rcp_f32_e32 v124, v124
	v_rcp_f32_e32 v125, v125
	v_exp_f32_e32 v128, v128
	v_exp_f32_e32 v129, v129
	v_lshlrev_b32_e32 v126, 16, v190
	v_and_b32_e32 v127, 0xffff0000, v190
	v_lshlrev_b32_e32 v130, 16, v186
	v_and_b32_e32 v131, 0xffff0000, v186
	v_pk_fma_f32 v[124:125], v[124:125], v[130:131], v[126:127]
	v_add_f32_e32 v126, 1.0, v128
	v_add_f32_e32 v127, 1.0, v129
	v_rcp_f32_e32 v126, v126
	v_rcp_f32_e32 v127, v127
	v_lshlrev_b32_e32 v128, 16, v191
	v_and_b32_e32 v129, 0xffff0000, v191
	v_lshlrev_b32_e32 v130, 16, v187
	v_and_b32_e32 v131, 0xffff0000, v187
	v_pk_fma_f32 v[126:127], v[126:127], v[130:131], v[128:129]
	v_lshl_add_u64 v[128:129], v[218:219], 2, s[10:11]
	v_lshl_add_u64 v[128:129], v[128:129], 0, v[246:247]
	v_pk_add_f32 v[116:117], v[116:117], v[68:69]
	s_nop 1
	v_permlane16_swap_b32 v120, v124
	v_permlane16_swap_b32 v121, v125
	v_permlane16_swap_b32 v122, v126
	v_permlane16_swap_b32 v123, v127
; DI float sigmoidf_(float x) { return __builtin_amdgcn_rcpf(1.f + __builtin_amdgcn_exp2f(fminf(-x * LOG2E, 126.f))); }
;     DI void operator()(const f32x4 (&acc)[2][2][4][2], const Unit& u, int wr, int wc, int fr, int fq) const {
;     ...
; #pragma unroll
;             for (int m = 0; m < 4; ++m)
; #pragma unroll
;                 for (int bj = 0; bj < 2; ++bj) {
;                     const size_t off = (size_t)(u.pm * 256 + ai * 128 + wr * 64 + m * 16 + fr) * DM + u.pn * 256 + bj * 128 + wc * 32 + 8 * fq;
;                     const u32x4 p = pw[m][bj], x = xw[m][bj];
;                     const f32x4 a0 = acc[ai][bj][m][0] + b0[bj], a1 = acc[ai][bj][m][1] + b1[bj];
;                     f32x4 x0, x1;
;                     x0[0] = bflo(x.x) + sigmoidf_(a0[0]) * bflo(p.x); x0[1] = bfhi(x.x) + sigmoidf_(a0[1]) * bfhi(p.x); x0[2] = bflo(x.y) + sigmoidf_(a0[2]) * bflo(p.y); x0[3] = bfhi(x.y) + sigmoidf_(a0[3]) * bfhi(p.y);
;                     x1[0] = bflo(x.z) + sigmoidf_(a1[0]) * bflo(p.z); x1[1] = bfhi(x.z) + sigmoidf_(a1[1]) * bfhi(p.z); x1[2] = bflo(x.w) + sigmoidf_(a1[2]) * bflo(p.w); x1[3] = bfhi(x.w) + sigmoidf_(a1[3]) * bfhi(p.w);
;                     *(f32x4*)(out + off) = x0; *(f32x4*)(out + off + 4) = x1;
	v_permlane32_swap_b32 v120, v124
	v_permlane32_swap_b32 v121, v125
	v_permlane32_swap_b32 v122, v126
	v_permlane32_swap_b32 v123, v127
	global_store_dwordx4 v[128:129], v[120:123], off
	global_store_dwordx4 v[128:129], v[124:127], off offset:64
	v_pk_add_f32 v[118:119], v[118:119], v[70:71]
	v_pk_add_f32 v[120:121], v[114:115], v[66:67]
	v_mul_f32_e32 v114, 0xbfb8aa3b, v116
	v_min_f32_e32 v114, 0x42fc0000, v114
	v_exp_f32_e32 v116, v114
	v_mul_f32_e32 v114, 0xbfb8aa3b, v117
	v_min_f32_e32 v114, 0x42fc0000, v114
	v_exp_f32_e32 v117, v114
	v_mul_f32_e32 v118, 0xbfb8aa3b, v118
	v_mul_f32_e32 v119, 0xbfb8aa3b, v119
	v_pk_add_f32 v[114:115], v[112:113], v[64:65]
	v_add_f32_e32 v112, 1.0, v116
	v_add_f32_e32 v113, 1.0, v117
	v_min_f32_e32 v118, 0x42fc0000, v118
	v_min_f32_e32 v119, 0x42fc0000, v119
	v_rcp_f32_e32 v112, v112
	v_rcp_f32_e32 v113, v113
	v_exp_f32_e32 v118, v118
	v_exp_f32_e32 v119, v119
	v_mul_f32_e32 v114, 0xbfb8aa3b, v114
	v_min_f32_e32 v114, 0x42fc0000, v114
	v_lshlrev_b32_e32 v116, 16, v180
	v_and_b32_e32 v117, 0xffff0000, v180
	v_lshlrev_b32_e32 v122, 16, v176
	v_and_b32_e32 v123, 0xffff0000, v176
	v_exp_f32_e32 v124, v114
	v_mul_f32_e32 v114, 0xbfb8aa3b, v115
	v_pk_fma_f32 v[112:113], v[112:113], v[122:123], v[116:117]
	v_add_f32_e32 v116, 1.0, v118
	v_add_f32_e32 v117, 1.0, v119
	v_min_f32_e32 v114, 0x42fc0000, v114
	v_rcp_f32_e32 v116, v116
	v_rcp_f32_e32 v117, v117
	v_exp_f32_e32 v125, v114
	v_lshlrev_b32_e32 v118, 16, v181
	v_and_b32_e32 v119, 0xffff0000, v181
	v_lshlrev_b32_e32 v122, 16, v177
	v_and_b32_e32 v123, 0xffff0000, v177
	v_mul_f32_e32 v120, 0xbfb8aa3b, v120
	v_mul_f32_e32 v121, 0xbfb8aa3b, v121
	v_pk_fma_f32 v[114:115], v[116:117], v[122:123], v[118:119]
	v_add_f32_e32 v116, 1.0, v124
	v_add_f32_e32 v117, 1.0, v125
	v_min_f32_e32 v120, 0x42fc0000, v120
	v_min_f32_e32 v121, 0x42fc0000, v121
	v_rcp_f32_e32 v116, v116
	v_rcp_f32_e32 v117, v117
	v_exp_f32_e32 v120, v120
	v_exp_f32_e32 v121, v121
	v_lshlrev_b32_e32 v118, 16, v182
	v_and_b32_e32 v119, 0xffff0000, v182
	v_lshlrev_b32_e32 v122, 16, v178
	v_and_b32_e32 v123, 0xffff0000, v178
	v_pk_fma_f32 v[116:117], v[116:117], v[122:123], v[118:119]
	v_add_f32_e32 v118, 1.0, v120
	v_add_f32_e32 v119, 1.0, v121
	v_rcp_f32_e32 v118, v118
	v_rcp_f32_e32 v119, v119
	v_lshlrev_b32_e32 v120, 16, v183
	v_and_b32_e32 v121, 0xffff0000, v183
	v_lshlrev_b32_e32 v122, 16, v179
	v_and_b32_e32 v123, 0xffff0000, v179
	v_pk_add_f32 v[108:109], v[108:109], v[76:77]
	v_pk_fma_f32 v[118:119], v[118:119], v[122:123], v[120:121]
	s_nop 1
	v_permlane16_swap_b32 v112, v116
	v_permlane16_swap_b32 v113, v117
	v_permlane16_swap_b32 v114, v118
	v_permlane16_swap_b32 v115, v119
	v_permlane32_swap_b32 v112, v116
	v_permlane32_swap_b32 v113, v117
	v_permlane32_swap_b32 v114, v118
	v_permlane32_swap_b32 v115, v119
	global_store_dwordx4 v[128:129], v[112:115], off offset:512
	global_store_dwordx4 v[128:129], v[116:119], off offset:576
	v_pk_add_f32 v[110:111], v[110:111], v[78:79]
	v_pk_add_f32 v[112:113], v[106:107], v[74:75]
	v_mul_f32_e32 v106, 0xbfb8aa3b, v108
	v_min_f32_e32 v106, 0x42fc0000, v106
	v_exp_f32_e32 v108, v106
	v_mul_f32_e32 v106, 0xbfb8aa3b, v109
	v_min_f32_e32 v106, 0x42fc0000, v106
	v_exp_f32_e32 v109, v106
	v_mul_f32_e32 v110, 0xbfb8aa3b, v110
	v_mul_f32_e32 v111, 0xbfb8aa3b, v111
	v_pk_add_f32 v[106:107], v[104:105], v[72:73]
	v_add_f32_e32 v104, 1.0, v108
	v_add_f32_e32 v105, 1.0, v109
	v_min_f32_e32 v110, 0x42fc0000, v110
	v_min_f32_e32 v111, 0x42fc0000, v111
	v_rcp_f32_e32 v104, v104
	v_rcp_f32_e32 v105, v105
	v_exp_f32_e32 v110, v110
	v_exp_f32_e32 v111, v111
	v_mul_f32_e32 v106, 0xbfb8aa3b, v106
	v_min_f32_e32 v106, 0x42fc0000, v106
	v_lshlrev_b32_e32 v108, 16, v172
	v_and_b32_e32 v109, 0xffff0000, v172
	v_lshlrev_b32_e32 v114, 16, v168
	v_and_b32_e32 v115, 0xffff0000, v168
	v_exp_f32_e32 v116, v106
	v_mul_f32_e32 v106, 0xbfb8aa3b, v107
	v_pk_fma_f32 v[104:105], v[104:105], v[114:115], v[108:109]
	v_add_f32_e32 v108, 1.0, v110
	v_add_f32_e32 v109, 1.0, v111
	v_min_f32_e32 v106, 0x42fc0000, v106
	v_rcp_f32_e32 v108, v108
	v_rcp_f32_e32 v109, v109
	v_exp_f32_e32 v117, v106
	v_lshlrev_b32_e32 v110, 16, v173
	v_and_b32_e32 v111, 0xffff0000, v173
	v_lshlrev_b32_e32 v114, 16, v169
	v_and_b32_e32 v115, 0xffff0000, v169
	v_mul_f32_e32 v112, 0xbfb8aa3b, v112
	v_mul_f32_e32 v113, 0xbfb8aa3b, v113
	v_pk_fma_f32 v[106:107], v[108:109], v[114:115], v[110:111]
	v_add_f32_e32 v108, 1.0, v116
	v_add_f32_e32 v109, 1.0, v117
	v_min_f32_e32 v112, 0x42fc0000, v112
	v_min_f32_e32 v113, 0x42fc0000, v113
	v_rcp_f32_e32 v108, v108
	v_rcp_f32_e32 v109, v109
	v_exp_f32_e32 v112, v112
	v_exp_f32_e32 v113, v113
	v_lshlrev_b32_e32 v110, 16, v174
	v_and_b32_e32 v111, 0xffff0000, v174
	v_lshlrev_b32_e32 v114, 16, v170
	v_and_b32_e32 v115, 0xffff0000, v170
	v_pk_fma_f32 v[108:109], v[108:109], v[114:115], v[110:111]
	v_add_f32_e32 v110, 1.0, v112
	v_add_f32_e32 v111, 1.0, v113
	v_rcp_f32_e32 v110, v110
	v_rcp_f32_e32 v111, v111
	v_lshlrev_b32_e32 v112, 16, v175
	v_and_b32_e32 v113, 0xffff0000, v175
	v_lshlrev_b32_e32 v114, 16, v171
	v_and_b32_e32 v115, 0xffff0000, v171
	v_pk_fma_f32 v[110:111], v[110:111], v[114:115], v[112:113]
	v_lshl_add_u64 v[112:113], v[216:217], 2, s[10:11]
	v_lshl_add_u64 v[112:113], v[112:113], 0, v[246:247]
	v_pk_add_f32 v[100:101], v[100:101], v[68:69]
	s_nop 1
	v_permlane16_swap_b32 v104, v108
	v_permlane16_swap_b32 v105, v109
	v_permlane16_swap_b32 v106, v110
	v_permlane16_swap_b32 v107, v111
	v_permlane32_swap_b32 v104, v108
	v_permlane32_swap_b32 v105, v109
	v_permlane32_swap_b32 v106, v110
	v_permlane32_swap_b32 v107, v111
	global_store_dwordx4 v[112:113], v[104:107], off
; DI float sigmoidf_(float x) { return __builtin_amdgcn_rcpf(1.f + __builtin_amdgcn_exp2f(fminf(-x * LOG2E, 126.f))); }
;     DI void operator()(const f32x4 (&acc)[2][2][4][2], const Unit& u, int wr, int wc, int fr, int fq) const {
;     ...
; #pragma unroll
;             for (int m = 0; m < 4; ++m)
; #pragma unroll
;                 for (int bj = 0; bj < 2; ++bj) {
;                     const size_t off = (size_t)(u.pm * 256 + ai * 128 + wr * 64 + m * 16 + fr) * DM + u.pn * 256 + bj * 128 + wc * 32 + 8 * fq;
;                     const u32x4 p = pw[m][bj], x = xw[m][bj];
;                     const f32x4 a0 = acc[ai][bj][m][0] + b0[bj], a1 = acc[ai][bj][m][1] + b1[bj];
;                     f32x4 x0, x1;
;                     x0[0] = bflo(x.x) + sigmoidf_(a0[0]) * bflo(p.x); x0[1] = bfhi(x.x) + sigmoidf_(a0[1]) * bfhi(p.x); x0[2] = bflo(x.y) + sigmoidf_(a0[2]) * bflo(p.y); x0[3] = bfhi(x.y) + sigmoidf_(a0[3]) * bfhi(p.y);
;                     x1[0] = bflo(x.z) + sigmoidf_(a1[0]) * bflo(p.z); x1[1] = bfhi(x.z) + sigmoidf_(a1[1]) * bfhi(p.z); x1[2] = bflo(x.w) + sigmoidf_(a1[2]) * bflo(p.w); x1[3] = bfhi(x.w) + sigmoidf_(a1[3]) * bfhi(p.w);
;                     *(f32x4*)(out + off) = x0; *(f32x4*)(out + off + 4) = x1;
	global_store_dwordx4 v[112:113], v[108:111], off offset:64
	v_pk_add_f32 v[102:103], v[102:103], v[70:71]
	v_pk_add_f32 v[104:105], v[98:99], v[66:67]
	v_mul_f32_e32 v98, 0xbfb8aa3b, v100
	v_min_f32_e32 v98, 0x42fc0000, v98
	v_exp_f32_e32 v100, v98
	v_mul_f32_e32 v98, 0xbfb8aa3b, v101
	v_min_f32_e32 v98, 0x42fc0000, v98
	v_exp_f32_e32 v101, v98
	v_mul_f32_e32 v102, 0xbfb8aa3b, v102
	v_mul_f32_e32 v103, 0xbfb8aa3b, v103
	v_pk_add_f32 v[98:99], v[96:97], v[64:65]
	v_add_f32_e32 v96, 1.0, v100
	v_add_f32_e32 v97, 1.0, v101
	v_min_f32_e32 v102, 0x42fc0000, v102
	v_min_f32_e32 v103, 0x42fc0000, v103
	v_rcp_f32_e32 v96, v96
	v_rcp_f32_e32 v97, v97
	v_exp_f32_e32 v102, v102
	v_exp_f32_e32 v103, v103
	v_mul_f32_e32 v98, 0xbfb8aa3b, v98
	v_min_f32_e32 v98, 0x42fc0000, v98
	v_lshlrev_b32_e32 v100, 16, v164
	v_and_b32_e32 v101, 0xffff0000, v164
	v_lshlrev_b32_e32 v106, 16, v160
	v_and_b32_e32 v107, 0xffff0000, v160
	v_exp_f32_e32 v108, v98
	v_mul_f32_e32 v98, 0xbfb8aa3b, v99
	v_pk_fma_f32 v[96:97], v[96:97], v[106:107], v[100:101]
	v_add_f32_e32 v100, 1.0, v102
	v_add_f32_e32 v101, 1.0, v103
	v_min_f32_e32 v98, 0x42fc0000, v98
	v_rcp_f32_e32 v100, v100
	v_rcp_f32_e32 v101, v101
	v_exp_f32_e32 v109, v98
	v_lshlrev_b32_e32 v102, 16, v165
	v_and_b32_e32 v103, 0xffff0000, v165
	v_lshlrev_b32_e32 v106, 16, v161
	v_and_b32_e32 v107, 0xffff0000, v161
	v_mul_f32_e32 v104, 0xbfb8aa3b, v104
	v_mul_f32_e32 v105, 0xbfb8aa3b, v105
	v_pk_fma_f32 v[98:99], v[100:101], v[106:107], v[102:103]
	v_add_f32_e32 v100, 1.0, v108
	v_add_f32_e32 v101, 1.0, v109
	v_min_f32_e32 v104, 0x42fc0000, v104
	v_min_f32_e32 v105, 0x42fc0000, v105
	v_rcp_f32_e32 v100, v100
	v_rcp_f32_e32 v101, v101
	v_exp_f32_e32 v104, v104
	v_exp_f32_e32 v105, v105
	v_lshlrev_b32_e32 v102, 16, v166
	v_and_b32_e32 v103, 0xffff0000, v166
	v_lshlrev_b32_e32 v106, 16, v162
	v_and_b32_e32 v107, 0xffff0000, v162
	v_pk_fma_f32 v[100:101], v[100:101], v[106:107], v[102:103]
	v_add_f32_e32 v102, 1.0, v104
	v_add_f32_e32 v103, 1.0, v105
	v_rcp_f32_e32 v102, v102
	v_rcp_f32_e32 v103, v103
	v_lshlrev_b32_e32 v104, 16, v167
	v_and_b32_e32 v105, 0xffff0000, v167
	v_lshlrev_b32_e32 v106, 16, v163
	v_and_b32_e32 v107, 0xffff0000, v163
	v_pk_add_f32 v[92:93], v[92:93], v[76:77]
	v_pk_fma_f32 v[102:103], v[102:103], v[106:107], v[104:105]
	s_nop 1
	v_permlane16_swap_b32 v96, v100
	v_permlane16_swap_b32 v97, v101
	v_permlane16_swap_b32 v98, v102
	v_permlane16_swap_b32 v99, v103
	v_permlane32_swap_b32 v96, v100
	v_permlane32_swap_b32 v97, v101
	v_permlane32_swap_b32 v98, v102
	v_permlane32_swap_b32 v99, v103
	global_store_dwordx4 v[112:113], v[96:99], off offset:512
	global_store_dwordx4 v[112:113], v[100:103], off offset:576
	v_pk_add_f32 v[94:95], v[94:95], v[78:79]
	v_pk_add_f32 v[96:97], v[90:91], v[74:75]
	v_mul_f32_e32 v90, 0xbfb8aa3b, v92
	v_min_f32_e32 v90, 0x42fc0000, v90
	v_exp_f32_e32 v92, v90
	v_mul_f32_e32 v90, 0xbfb8aa3b, v93
	v_min_f32_e32 v90, 0x42fc0000, v90
	v_exp_f32_e32 v93, v90
	v_mul_f32_e32 v94, 0xbfb8aa3b, v94
	v_mul_f32_e32 v95, 0xbfb8aa3b, v95
	v_pk_add_f32 v[90:91], v[88:89], v[72:73]
	v_add_f32_e32 v88, 1.0, v92
	v_add_f32_e32 v89, 1.0, v93
	v_min_f32_e32 v94, 0x42fc0000, v94
	v_min_f32_e32 v95, 0x42fc0000, v95
	v_rcp_f32_e32 v88, v88
	v_rcp_f32_e32 v89, v89
	v_exp_f32_e32 v94, v94
	v_exp_f32_e32 v95, v95
	v_mul_f32_e32 v90, 0xbfb8aa3b, v90
	v_min_f32_e32 v90, 0x42fc0000, v90
	v_lshlrev_b32_e32 v92, 16, v156
	v_and_b32_e32 v93, 0xffff0000, v156
	v_lshlrev_b32_e32 v98, 16, v152
	v_and_b32_e32 v99, 0xffff0000, v152
	v_exp_f32_e32 v100, v90
	v_mul_f32_e32 v90, 0xbfb8aa3b, v91
	v_pk_fma_f32 v[88:89], v[88:89], v[98:99], v[92:93]
	v_add_f32_e32 v92, 1.0, v94
	v_add_f32_e32 v93, 1.0, v95
	v_min_f32_e32 v90, 0x42fc0000, v90
	v_rcp_f32_e32 v92, v92
	v_rcp_f32_e32 v93, v93
	v_exp_f32_e32 v101, v90
	v_lshlrev_b32_e32 v94, 16, v157
	v_and_b32_e32 v95, 0xffff0000, v157
	v_lshlrev_b32_e32 v98, 16, v153
	v_and_b32_e32 v99, 0xffff0000, v153
	v_mul_f32_e32 v96, 0xbfb8aa3b, v96
	v_mul_f32_e32 v97, 0xbfb8aa3b, v97
	v_pk_fma_f32 v[90:91], v[92:93], v[98:99], v[94:95]
	v_add_f32_e32 v92, 1.0, v100
	v_add_f32_e32 v93, 1.0, v101
	v_min_f32_e32 v96, 0x42fc0000, v96
	v_min_f32_e32 v97, 0x42fc0000, v97
	v_rcp_f32_e32 v92, v92
	v_rcp_f32_e32 v93, v93
	v_exp_f32_e32 v96, v96
	v_exp_f32_e32 v97, v97
	v_lshlrev_b32_e32 v94, 16, v158
	v_and_b32_e32 v95, 0xffff0000, v158
	v_lshlrev_b32_e32 v98, 16, v154
	v_and_b32_e32 v99, 0xffff0000, v154
	v_pk_fma_f32 v[92:93], v[92:93], v[98:99], v[94:95]
	v_add_f32_e32 v94, 1.0, v96
	v_add_f32_e32 v95, 1.0, v97
	v_rcp_f32_e32 v94, v94
	v_rcp_f32_e32 v95, v95
	v_lshlrev_b32_e32 v96, 16, v159
	v_and_b32_e32 v97, 0xffff0000, v159
	v_lshlrev_b32_e32 v98, 16, v155
	v_and_b32_e32 v99, 0xffff0000, v155
	v_pk_fma_f32 v[94:95], v[94:95], v[98:99], v[96:97]
	v_lshl_add_u64 v[96:97], v[214:215], 2, s[10:11]
	v_lshl_add_u64 v[96:97], v[96:97], 0, v[246:247]
	v_pk_add_f32 v[84:85], v[84:85], v[68:69]
	s_nop 1
	v_permlane16_swap_b32 v88, v92
	v_permlane16_swap_b32 v89, v93
	v_permlane16_swap_b32 v90, v94
	v_permlane16_swap_b32 v91, v95
	v_permlane32_swap_b32 v88, v92
	v_permlane32_swap_b32 v89, v93
	v_permlane32_swap_b32 v90, v94
	v_permlane32_swap_b32 v91, v95
	global_store_dwordx4 v[96:97], v[88:91], off
	global_store_dwordx4 v[96:97], v[92:95], off offset:64
	v_pk_add_f32 v[86:87], v[86:87], v[70:71]
	v_pk_add_f32 v[88:89], v[82:83], v[66:67]
	v_mul_f32_e32 v82, 0xbfb8aa3b, v84
	v_min_f32_e32 v82, 0x42fc0000, v82
	v_exp_f32_e32 v84, v82
	v_mul_f32_e32 v82, 0xbfb8aa3b, v85
	v_min_f32_e32 v82, 0x42fc0000, v82
	v_exp_f32_e32 v85, v82
	v_mul_f32_e32 v86, 0xbfb8aa3b, v86
	v_mul_f32_e32 v87, 0xbfb8aa3b, v87
; DI float sigmoidf_(float x) { return __builtin_amdgcn_rcpf(1.f + __builtin_amdgcn_exp2f(fminf(-x * LOG2E, 126.f))); }
;     DI void operator()(const f32x4 (&acc)[2][2][4][2], const Unit& u, int wr, int wc, int fr, int fq) const {
;     ...
;         for (int ai = 0; ai < 2; ++ai) {
;             u32x4 pw[4][2], xw[4][2];
; #pragma unroll
;             for (int m = 0; m < 4; ++m)
; #pragma unroll
;                 for (int bj = 0; bj < 2; ++bj) {
;                     const size_t off = (size_t)(u.pm * 256 + ai * 128 + wr * 64 + m * 16 + fr) * DM + u.pn * 256 + bj * 128 + wc * 32 + 8 * fq;
;                     pw[m][bj] = *(const u32x4*)(pp + off); xw[m][bj] = *(const u32x4*)(xb + off);
;                 }
; #pragma unroll
;             for (int m = 0; m < 4; ++m)
; #pragma unroll
;                 for (int bj = 0; bj < 2; ++bj) {
;                     const size_t off = (size_t)(u.pm * 256 + ai * 128 + wr * 64 + m * 16 + fr) * DM + u.pn * 256 + bj * 128 + wc * 32 + 8 * fq;
;                     const u32x4 p = pw[m][bj], x = xw[m][bj];
;                     const f32x4 a0 = acc[ai][bj][m][0] + b0[bj], a1 = acc[ai][bj][m][1] + b1[bj];
;                     f32x4 x0, x1;
;                     x0[0] = bflo(x.x) + sigmoidf_(a0[0]) * bflo(p.x); x0[1] = bfhi(x.x) + sigmoidf_(a0[1]) * bfhi(p.x); x0[2] = bflo(x.y) + sigmoidf_(a0[2]) * bflo(p.y); x0[3] = bfhi(x.y) + sigmoidf_(a0[3]) * bfhi(p.y);
;                     x1[0] = bflo(x.z) + sigmoidf_(a1[0]) * bflo(p.z); x1[1] = bfhi(x.z) + sigmoidf_(a1[1]) * bfhi(p.z); x1[2] = bflo(x.w) + sigmoidf_(a1[2]) * bflo(p.w); x1[3] = bfhi(x.w) + sigmoidf_(a1[3]) * bfhi(p.w);
;                     *(f32x4*)(out + off) = x0; *(f32x4*)(out + off + 4) = x1;
	v_pk_add_f32 v[82:83], v[80:81], v[64:65]
	v_add_f32_e32 v80, 1.0, v84
	v_add_f32_e32 v81, 1.0, v85
	v_min_f32_e32 v86, 0x42fc0000, v86
	v_min_f32_e32 v87, 0x42fc0000, v87
	v_rcp_f32_e32 v80, v80
	v_rcp_f32_e32 v81, v81
	v_exp_f32_e32 v86, v86
	v_exp_f32_e32 v87, v87
	v_mul_f32_e32 v82, 0xbfb8aa3b, v82
	v_min_f32_e32 v82, 0x42fc0000, v82
	v_lshlrev_b32_e32 v84, 16, v140
	v_and_b32_e32 v85, 0xffff0000, v140
	v_lshlrev_b32_e32 v90, 16, v136
	v_and_b32_e32 v91, 0xffff0000, v136
	v_exp_f32_e32 v92, v82
	v_mul_f32_e32 v82, 0xbfb8aa3b, v83
	v_pk_fma_f32 v[80:81], v[80:81], v[90:91], v[84:85]
	v_add_f32_e32 v84, 1.0, v86
	v_add_f32_e32 v85, 1.0, v87
	v_min_f32_e32 v82, 0x42fc0000, v82
	v_rcp_f32_e32 v84, v84
	v_rcp_f32_e32 v85, v85
	v_exp_f32_e32 v93, v82
	v_lshlrev_b32_e32 v86, 16, v141
	v_and_b32_e32 v87, 0xffff0000, v141
	v_lshlrev_b32_e32 v90, 16, v137
	v_and_b32_e32 v91, 0xffff0000, v137
	v_mul_f32_e32 v88, 0xbfb8aa3b, v88
	v_mul_f32_e32 v89, 0xbfb8aa3b, v89
	v_pk_fma_f32 v[82:83], v[84:85], v[90:91], v[86:87]
	v_add_f32_e32 v84, 1.0, v92
	v_add_f32_e32 v85, 1.0, v93
	v_min_f32_e32 v88, 0x42fc0000, v88
	v_min_f32_e32 v89, 0x42fc0000, v89
	v_rcp_f32_e32 v84, v84
	v_rcp_f32_e32 v85, v85
	v_exp_f32_e32 v88, v88
	v_exp_f32_e32 v89, v89
	v_lshlrev_b32_e32 v86, 16, v142
	v_and_b32_e32 v87, 0xffff0000, v142
	v_lshlrev_b32_e32 v90, 16, v138
	v_and_b32_e32 v91, 0xffff0000, v138
	v_pk_fma_f32 v[84:85], v[84:85], v[90:91], v[86:87]
	v_add_f32_e32 v86, 1.0, v88
	v_add_f32_e32 v87, 1.0, v89
	v_rcp_f32_e32 v86, v86
	v_rcp_f32_e32 v87, v87
	v_lshlrev_b32_e32 v88, 16, v143
	v_and_b32_e32 v89, 0xffff0000, v143
	v_lshlrev_b32_e32 v90, 16, v139
	v_and_b32_e32 v91, 0xffff0000, v139
	v_pk_fma_f32 v[86:87], v[86:87], v[90:91], v[88:89]
	s_nop 1
	v_permlane16_swap_b32 v80, v84
	v_permlane16_swap_b32 v81, v85
	v_permlane16_swap_b32 v82, v86
	v_permlane16_swap_b32 v83, v87
	v_permlane32_swap_b32 v80, v84
	v_permlane32_swap_b32 v81, v85
	v_permlane32_swap_b32 v82, v86
	v_permlane32_swap_b32 v83, v87
	global_store_dwordx4 v[96:97], v[80:83], off offset:512
	global_store_dwordx4 v[96:97], v[84:87], off offset:576
	v_pk_add_f32 v[60:61], v[60:61], v[76:77]
	v_add_u32_e32 v80, 0x80, v212
	v_ashrrev_i32_e32 v81, 31, v80
	v_lshlrev_b64 v[80:81], 10, v[80:81]
	v_lshl_add_u64 v[150:151], v[80:81], 0, v[210:211]
	v_lshlrev_b64 v[80:81], 1, v[150:151]
	v_lshl_add_u64 v[82:83], s[16:17], 0, v[80:81]
	global_load_dwordx4 v[142:145], v[82:83], off
	v_lshl_add_u64 v[82:83], s[24:25], 0, v[80:81]
	global_load_dwordx4 v[146:149], v[82:83], off
	v_or_b32_e32 v80, 0x100, v80
	v_lshl_add_u64 v[82:83], s[24:25], 0, v[80:81]
	v_lshl_add_u64 v[80:81], s[16:17], 0, v[80:81]
	global_load_dwordx4 v[128:131], v[82:83], off
	global_load_dwordx4 v[132:135], v[80:81], off
	v_add_u32_e32 v80, 0x90, v212
	v_ashrrev_i32_e32 v81, 31, v80
	v_lshlrev_b64 v[80:81], 10, v[80:81]
	v_lshl_add_u64 v[140:141], v[80:81], 0, v[210:211]
	v_lshlrev_b64 v[80:81], 1, v[140:141]
	v_lshl_add_u64 v[82:83], s[24:25], 0, v[80:81]
	v_lshl_add_u64 v[84:85], s[16:17], 0, v[80:81]
	global_load_dwordx4 v[120:123], v[82:83], off
	global_load_dwordx4 v[124:127], v[84:85], off
	v_pk_add_f32 v[152:153], v[58:59], v[74:75]
	v_mul_f32_e32 v58, 0xbfb8aa3b, v60
	v_min_f32_e32 v58, 0x42fc0000, v58
	v_exp_f32_e32 v60, v58
	v_mul_f32_e32 v58, 0xbfb8aa3b, v61
	v_min_f32_e32 v58, 0x42fc0000, v58
	v_exp_f32_e32 v61, v58
	v_pk_add_f32 v[62:63], v[62:63], v[78:79]
	v_pk_add_f32 v[58:59], v[56:57], v[72:73]
	v_mul_f32_e32 v62, 0xbfb8aa3b, v62
	v_mul_f32_e32 v63, 0xbfb8aa3b, v63
	v_add_f32_e32 v56, 1.0, v60
	v_add_f32_e32 v57, 1.0, v61
	v_min_f32_e32 v62, 0x42fc0000, v62
	v_min_f32_e32 v63, 0x42fc0000, v63
	v_rcp_f32_e32 v56, v56
	v_rcp_f32_e32 v57, v57
	v_exp_f32_e32 v62, v62
	v_exp_f32_e32 v63, v63
	v_mul_f32_e32 v58, 0xbfb8aa3b, v58
	v_min_f32_e32 v58, 0x42fc0000, v58
	v_or_b32_e32 v80, 0x100, v80
	v_lshl_add_u64 v[82:83], s[24:25], 0, v[80:81]
	v_lshl_add_u64 v[80:81], s[16:17], 0, v[80:81]
	global_load_dwordx4 v[112:115], v[82:83], off
	global_load_dwordx4 v[116:119], v[80:81], off
	v_add_u32_e32 v80, 0xa0, v212
	v_ashrrev_i32_e32 v81, 31, v80
	v_lshlrev_b64 v[80:81], 10, v[80:81]
	v_lshl_add_u64 v[138:139], v[80:81], 0, v[210:211]
	v_lshlrev_b64 v[80:81], 1, v[138:139]
	v_lshl_add_u64 v[82:83], s[24:25], 0, v[80:81]
	v_lshl_add_u64 v[84:85], s[16:17], 0, v[80:81]
	v_or_b32_e32 v80, 0x100, v80
	global_load_dwordx4 v[104:107], v[82:83], off
	global_load_dwordx4 v[108:111], v[84:85], off
	v_lshl_add_u64 v[82:83], s[24:25], 0, v[80:81]
	v_lshl_add_u64 v[80:81], s[16:17], 0, v[80:81]
	global_load_dwordx4 v[96:99], v[82:83], off
	global_load_dwordx4 v[100:103], v[80:81], off
	v_add_u32_e32 v80, 0xb0, v212
	v_ashrrev_i32_e32 v81, 31, v80
	v_lshlrev_b64 v[80:81], 10, v[80:81]
	v_lshl_add_u64 v[136:137], v[80:81], 0, v[210:211]
	v_lshlrev_b64 v[80:81], 1, v[136:137]
	v_lshl_add_u64 v[82:83], s[24:25], 0, v[80:81]
	v_lshl_add_u64 v[84:85], s[16:17], 0, v[80:81]
	v_or_b32_e32 v80, 0x100, v80
	global_load_dwordx4 v[88:91], v[82:83], off
	global_load_dwordx4 v[92:95], v[84:85], off
	v_lshl_add_u64 v[82:83], s[24:25], 0, v[80:81]
	v_lshl_add_u64 v[84:85], s[16:17], 0, v[80:81]
	v_pk_add_f32 v[52:53], v[52:53], v[68:69]
	global_load_dwordx4 v[80:83], v[82:83], off
	s_nop 0
	global_load_dwordx4 v[84:87], v[84:85], off
	v_pk_add_f32 v[54:55], v[54:55], v[70:71]
	v_pk_add_f32 v[44:45], v[44:45], v[76:77]
	v_mul_f32_e32 v54, 0xbfb8aa3b, v54
	v_mul_f32_e32 v55, 0xbfb8aa3b, v55
	v_min_f32_e32 v54, 0x42fc0000, v54
	v_min_f32_e32 v55, 0x42fc0000, v55
	v_exp_f32_e32 v54, v54
	v_exp_f32_e32 v55, v55
	v_pk_add_f32 v[46:47], v[46:47], v[78:79]
	v_pk_add_f32 v[36:37], v[36:37], v[68:69]
	v_mul_f32_e32 v46, 0xbfb8aa3b, v46
	v_mul_f32_e32 v47, 0xbfb8aa3b, v47
	v_min_f32_e32 v46, 0x42fc0000, v46
	v_min_f32_e32 v47, 0x42fc0000, v47
	v_exp_f32_e32 v46, v46
	s_waitcnt vmcnt(15)
; DI float sigmoidf_(float x) { return __builtin_amdgcn_rcpf(1.f + __builtin_amdgcn_exp2f(fminf(-x * LOG2E, 126.f))); }
;     DI void operator()(const f32x4 (&acc)[2][2][4][2], const Unit& u, int wr, int wc, int fr, int fq) const {
;     ...
; #pragma unroll
;             for (int m = 0; m < 4; ++m)
; #pragma unroll
;                 for (int bj = 0; bj < 2; ++bj) {
;                     const size_t off = (size_t)(u.pm * 256 + ai * 128 + wr * 64 + m * 16 + fr) * DM + u.pn * 256 + bj * 128 + wc * 32 + 8 * fq;
;                     const u32x4 p = pw[m][bj], x = xw[m][bj];
;                     const f32x4 a0 = acc[ai][bj][m][0] + b0[bj], a1 = acc[ai][bj][m][1] + b1[bj];
;                     f32x4 x0, x1;
;                     x0[0] = bflo(x.x) + sigmoidf_(a0[0]) * bflo(p.x); x0[1] = bfhi(x.x) + sigmoidf_(a0[1]) * bfhi(p.x); x0[2] = bflo(x.y) + sigmoidf_(a0[2]) * bflo(p.y); x0[3] = bfhi(x.y) + sigmoidf_(a0[3]) * bfhi(p.y);
;                     x1[0] = bflo(x.z) + sigmoidf_(a1[0]) * bflo(p.z); x1[1] = bfhi(x.z) + sigmoidf_(a1[1]) * bfhi(p.z); x1[2] = bflo(x.w) + sigmoidf_(a1[2]) * bflo(p.w); x1[3] = bfhi(x.w) + sigmoidf_(a1[3]) * bfhi(p.w);
;                     *(f32x4*)(out + off) = x0; *(f32x4*)(out + off + 4) = x1;
	v_lshlrev_b32_e32 v60, 16, v142
	v_and_b32_e32 v61, 0xffff0000, v142
	s_waitcnt vmcnt(14)
	v_lshlrev_b32_e32 v154, 16, v146
	v_and_b32_e32 v155, 0xffff0000, v146
	v_pk_fma_f32 v[56:57], v[56:57], v[154:155], v[60:61]
	v_add_f32_e32 v60, 1.0, v62
	v_add_f32_e32 v61, 1.0, v63
	v_exp_f32_e32 v146, v58
	v_mul_f32_e32 v58, 0xbfb8aa3b, v59
	v_rcp_f32_e32 v60, v60
	v_rcp_f32_e32 v61, v61
	v_min_f32_e32 v58, 0x42fc0000, v58
	v_lshlrev_b32_e32 v62, 16, v143
	v_and_b32_e32 v63, 0xffff0000, v143
	v_lshlrev_b32_e32 v142, 16, v147
	v_and_b32_e32 v143, 0xffff0000, v147
	v_exp_f32_e32 v147, v58
	v_pk_fma_f32 v[58:59], v[60:61], v[142:143], v[62:63]
	v_add_f32_e32 v60, 1.0, v146
	v_lshlrev_b32_e32 v62, 16, v144
	v_and_b32_e32 v63, 0xffff0000, v144
	v_mul_f32_e32 v144, 0xbfb8aa3b, v152
	v_mul_f32_e32 v146, 0xbfb8aa3b, v153
	v_add_f32_e32 v61, 1.0, v147
	v_min_f32_e32 v144, 0x42fc0000, v144
	v_min_f32_e32 v146, 0x42fc0000, v146
	v_rcp_f32_e32 v60, v60
	v_rcp_f32_e32 v61, v61
	v_exp_f32_e32 v144, v144
	v_exp_f32_e32 v146, v146
	v_lshlrev_b32_e32 v142, 16, v148
	v_and_b32_e32 v143, 0xffff0000, v148
	v_pk_fma_f32 v[60:61], v[60:61], v[142:143], v[62:63]
	v_add_f32_e32 v62, 1.0, v144
	v_add_f32_e32 v63, 1.0, v146
	v_rcp_f32_e32 v62, v62
	v_rcp_f32_e32 v63, v63
	v_lshlrev_b32_e32 v142, 16, v145
	v_and_b32_e32 v143, 0xffff0000, v145
	v_lshlrev_b32_e32 v144, 16, v149
	v_and_b32_e32 v145, 0xffff0000, v149
	v_pk_fma_f32 v[62:63], v[62:63], v[144:145], v[142:143]
	v_lshl_add_u64 v[142:143], v[150:151], 2, s[10:11]
	v_lshl_add_u64 v[142:143], v[142:143], 0, v[246:247]
	s_nop 1
	v_permlane16_swap_b32 v56, v60
	v_permlane16_swap_b32 v57, v61
	v_permlane16_swap_b32 v58, v62
	v_permlane16_swap_b32 v59, v63
	v_permlane32_swap_b32 v56, v60
	v_permlane32_swap_b32 v57, v61
	v_permlane32_swap_b32 v58, v62
	v_permlane32_swap_b32 v59, v63
	global_store_dwordx4 v[142:143], v[56:59], off
	global_store_dwordx4 v[142:143], v[60:63], off offset:64
	v_exp_f32_e32 v47, v47
	v_pk_add_f32 v[56:57], v[50:51], v[66:67]
	v_mul_f32_e32 v50, 0xbfb8aa3b, v52
	v_min_f32_e32 v50, 0x42fc0000, v50
	v_exp_f32_e32 v52, v50
	v_mul_f32_e32 v50, 0xbfb8aa3b, v53
	v_min_f32_e32 v50, 0x42fc0000, v50
	v_exp_f32_e32 v53, v50
	v_pk_add_f32 v[50:51], v[48:49], v[64:65]
	v_add_f32_e32 v48, 1.0, v52
	v_rcp_f32_e32 v48, v48
	v_add_f32_e32 v49, 1.0, v53
	v_rcp_f32_e32 v49, v49
	v_mul_f32_e32 v50, 0xbfb8aa3b, v50
	v_min_f32_e32 v50, 0x42fc0000, v50
	s_waitcnt vmcnt(14)
	v_lshlrev_b32_e32 v52, 16, v132
	v_and_b32_e32 v53, 0xffff0000, v132
	v_lshlrev_b32_e32 v58, 16, v128
	v_and_b32_e32 v59, 0xffff0000, v128
	v_exp_f32_e32 v60, v50
	v_mul_f32_e32 v50, 0xbfb8aa3b, v51
	v_pk_fma_f32 v[48:49], v[48:49], v[58:59], v[52:53]
	v_add_f32_e32 v52, 1.0, v54
	v_add_f32_e32 v53, 1.0, v55
	v_min_f32_e32 v50, 0x42fc0000, v50
	v_rcp_f32_e32 v52, v52
	v_rcp_f32_e32 v53, v53
	v_exp_f32_e32 v61, v50
	v_lshlrev_b32_e32 v54, 16, v133
	v_and_b32_e32 v55, 0xffff0000, v133
	v_lshlrev_b32_e32 v58, 16, v129
	v_and_b32_e32 v59, 0xffff0000, v129
	v_mul_f32_e32 v56, 0xbfb8aa3b, v56
	v_mul_f32_e32 v57, 0xbfb8aa3b, v57
	v_pk_fma_f32 v[50:51], v[52:53], v[58:59], v[54:55]
	v_add_f32_e32 v52, 1.0, v60
	v_add_f32_e32 v53, 1.0, v61
	v_min_f32_e32 v56, 0x42fc0000, v56
	v_min_f32_e32 v57, 0x42fc0000, v57
	v_rcp_f32_e32 v52, v52
	v_rcp_f32_e32 v53, v53
	v_exp_f32_e32 v56, v56
	v_exp_f32_e32 v57, v57
	v_lshlrev_b32_e32 v54, 16, v134
	v_and_b32_e32 v55, 0xffff0000, v134
	v_lshlrev_b32_e32 v58, 16, v130
	v_and_b32_e32 v59, 0xffff0000, v130
	v_pk_fma_f32 v[52:53], v[52:53], v[58:59], v[54:55]
	v_add_f32_e32 v54, 1.0, v56
	v_add_f32_e32 v55, 1.0, v57
	v_rcp_f32_e32 v54, v54
	v_rcp_f32_e32 v55, v55
	v_lshlrev_b32_e32 v56, 16, v135
	v_and_b32_e32 v57, 0xffff0000, v135
	v_lshlrev_b32_e32 v58, 16, v131
	v_and_b32_e32 v59, 0xffff0000, v131
	v_pk_fma_f32 v[54:55], v[54:55], v[58:59], v[56:57]
	s_nop 1
	v_permlane16_swap_b32 v48, v52
	v_permlane16_swap_b32 v49, v53
	v_permlane16_swap_b32 v50, v54
	v_permlane16_swap_b32 v51, v55
	v_permlane32_swap_b32 v48, v52
	v_permlane32_swap_b32 v49, v53
	v_permlane32_swap_b32 v50, v54
	v_permlane32_swap_b32 v51, v55
	global_store_dwordx4 v[142:143], v[48:51], off offset:512
	global_store_dwordx4 v[142:143], v[52:55], off offset:576
	v_pk_add_f32 v[38:39], v[38:39], v[70:71]
	v_pk_add_f32 v[48:49], v[42:43], v[74:75]
	v_mul_f32_e32 v42, 0xbfb8aa3b, v44
	v_min_f32_e32 v42, 0x42fc0000, v42
	v_exp_f32_e32 v44, v42
	v_mul_f32_e32 v42, 0xbfb8aa3b, v45
	v_min_f32_e32 v42, 0x42fc0000, v42
	v_exp_f32_e32 v45, v42
	v_pk_add_f32 v[42:43], v[40:41], v[72:73]
	v_add_f32_e32 v40, 1.0, v44
	v_rcp_f32_e32 v40, v40
	v_add_f32_e32 v41, 1.0, v45
	v_rcp_f32_e32 v41, v41
	v_mul_f32_e32 v42, 0xbfb8aa3b, v42
	v_min_f32_e32 v42, 0x42fc0000, v42
	s_waitcnt vmcnt(14)
; DI float sigmoidf_(float x) { return __builtin_amdgcn_rcpf(1.f + __builtin_amdgcn_exp2f(fminf(-x * LOG2E, 126.f))); }
;     DI void operator()(const f32x4 (&acc)[2][2][4][2], const Unit& u, int wr, int wc, int fr, int fq) const {
;     ...
; #pragma unroll
;             for (int m = 0; m < 4; ++m)
; #pragma unroll
;                 for (int bj = 0; bj < 2; ++bj) {
;                     const size_t off = (size_t)(u.pm * 256 + ai * 128 + wr * 64 + m * 16 + fr) * DM + u.pn * 256 + bj * 128 + wc * 32 + 8 * fq;
;                     const u32x4 p = pw[m][bj], x = xw[m][bj];
;                     const f32x4 a0 = acc[ai][bj][m][0] + b0[bj], a1 = acc[ai][bj][m][1] + b1[bj];
;                     f32x4 x0, x1;
;                     x0[0] = bflo(x.x) + sigmoidf_(a0[0]) * bflo(p.x); x0[1] = bfhi(x.x) + sigmoidf_(a0[1]) * bfhi(p.x); x0[2] = bflo(x.y) + sigmoidf_(a0[2]) * bflo(p.y); x0[3] = bfhi(x.y) + sigmoidf_(a0[3]) * bfhi(p.y);
;                     x1[0] = bflo(x.z) + sigmoidf_(a1[0]) * bflo(p.z); x1[1] = bfhi(x.z) + sigmoidf_(a1[1]) * bfhi(p.z); x1[2] = bflo(x.w) + sigmoidf_(a1[2]) * bflo(p.w); x1[3] = bfhi(x.w) + sigmoidf_(a1[3]) * bfhi(p.w);
;                     *(f32x4*)(out + off) = x0; *(f32x4*)(out + off + 4) = x1;
	v_lshlrev_b32_e32 v44, 16, v124
	v_and_b32_e32 v45, 0xffff0000, v124
	v_lshlrev_b32_e32 v50, 16, v120
	v_and_b32_e32 v51, 0xffff0000, v120
	v_exp_f32_e32 v52, v42
	v_mul_f32_e32 v42, 0xbfb8aa3b, v43
	v_pk_fma_f32 v[40:41], v[40:41], v[50:51], v[44:45]
	v_add_f32_e32 v44, 1.0, v46
	v_add_f32_e32 v45, 1.0, v47
	v_min_f32_e32 v42, 0x42fc0000, v42
	v_rcp_f32_e32 v44, v44
	v_rcp_f32_e32 v45, v45
	v_exp_f32_e32 v53, v42
	v_lshlrev_b32_e32 v46, 16, v125
	v_and_b32_e32 v47, 0xffff0000, v125
	v_lshlrev_b32_e32 v50, 16, v121
	v_and_b32_e32 v51, 0xffff0000, v121
	v_mul_f32_e32 v48, 0xbfb8aa3b, v48
	v_mul_f32_e32 v49, 0xbfb8aa3b, v49
	v_pk_fma_f32 v[42:43], v[44:45], v[50:51], v[46:47]
	v_add_f32_e32 v44, 1.0, v52
	v_add_f32_e32 v45, 1.0, v53
	v_min_f32_e32 v48, 0x42fc0000, v48
	v_min_f32_e32 v49, 0x42fc0000, v49
	v_rcp_f32_e32 v44, v44
	v_rcp_f32_e32 v45, v45
	v_exp_f32_e32 v48, v48
	v_exp_f32_e32 v49, v49
	v_lshlrev_b32_e32 v46, 16, v126
	v_and_b32_e32 v47, 0xffff0000, v126
	v_lshlrev_b32_e32 v50, 16, v122
	v_and_b32_e32 v51, 0xffff0000, v122
	v_pk_fma_f32 v[44:45], v[44:45], v[50:51], v[46:47]
	v_add_f32_e32 v46, 1.0, v48
	v_add_f32_e32 v47, 1.0, v49
	v_rcp_f32_e32 v46, v46
	v_rcp_f32_e32 v47, v47
	v_lshlrev_b32_e32 v48, 16, v127
	v_and_b32_e32 v49, 0xffff0000, v127
	v_lshlrev_b32_e32 v50, 16, v123
	v_and_b32_e32 v51, 0xffff0000, v123
	v_pk_fma_f32 v[46:47], v[46:47], v[50:51], v[48:49]
	v_lshl_add_u64 v[48:49], v[140:141], 2, s[10:11]
	v_lshl_add_u64 v[48:49], v[48:49], 0, v[246:247]
	s_nop 1
	v_permlane16_swap_b32 v40, v44
	v_permlane16_swap_b32 v41, v45
	v_permlane16_swap_b32 v42, v46
	v_permlane16_swap_b32 v43, v47
	v_permlane32_swap_b32 v40, v44
	v_permlane32_swap_b32 v41, v45
	v_permlane32_swap_b32 v42, v46
	v_permlane32_swap_b32 v43, v47
	global_store_dwordx4 v[48:49], v[40:43], off
	global_store_dwordx4 v[48:49], v[44:47], off offset:64
	v_mul_f32_e32 v38, 0xbfb8aa3b, v38
	v_pk_add_f32 v[40:41], v[34:35], v[66:67]
	v_mul_f32_e32 v34, 0xbfb8aa3b, v36
	v_min_f32_e32 v34, 0x42fc0000, v34
	v_exp_f32_e32 v36, v34
	v_mul_f32_e32 v34, 0xbfb8aa3b, v37
	v_min_f32_e32 v34, 0x42fc0000, v34
	v_exp_f32_e32 v37, v34
	v_mul_f32_e32 v39, 0xbfb8aa3b, v39
	v_pk_add_f32 v[34:35], v[32:33], v[64:65]
	v_add_f32_e32 v32, 1.0, v36
	v_add_f32_e32 v33, 1.0, v37
	v_min_f32_e32 v38, 0x42fc0000, v38
	v_min_f32_e32 v39, 0x42fc0000, v39
	v_rcp_f32_e32 v32, v32
	v_rcp_f32_e32 v33, v33
	v_exp_f32_e32 v38, v38
	v_exp_f32_e32 v39, v39
	v_mul_f32_e32 v34, 0xbfb8aa3b, v34
	v_min_f32_e32 v34, 0x42fc0000, v34
	s_waitcnt vmcnt(14)
	v_lshlrev_b32_e32 v36, 16, v116
	v_and_b32_e32 v37, 0xffff0000, v116
	v_lshlrev_b32_e32 v42, 16, v112
	v_and_b32_e32 v43, 0xffff0000, v112
	v_exp_f32_e32 v44, v34
	v_mul_f32_e32 v34, 0xbfb8aa3b, v35
	v_pk_fma_f32 v[32:33], v[32:33], v[42:43], v[36:37]
	v_add_f32_e32 v36, 1.0, v38
	v_add_f32_e32 v37, 1.0, v39
	v_min_f32_e32 v34, 0x42fc0000, v34
	v_rcp_f32_e32 v36, v36
	v_rcp_f32_e32 v37, v37
	v_exp_f32_e32 v45, v34
	v_lshlrev_b32_e32 v38, 16, v117
	v_and_b32_e32 v39, 0xffff0000, v117
	v_lshlrev_b32_e32 v42, 16, v113
	v_and_b32_e32 v43, 0xffff0000, v113
	v_mul_f32_e32 v40, 0xbfb8aa3b, v40
	v_mul_f32_e32 v41, 0xbfb8aa3b, v41
	v_pk_fma_f32 v[34:35], v[36:37], v[42:43], v[38:39]
	v_add_f32_e32 v36, 1.0, v44
	v_add_f32_e32 v37, 1.0, v45
	v_min_f32_e32 v40, 0x42fc0000, v40
	v_min_f32_e32 v41, 0x42fc0000, v41
	v_rcp_f32_e32 v36, v36
	v_rcp_f32_e32 v37, v37
	v_exp_f32_e32 v40, v40
	v_exp_f32_e32 v41, v41
	v_lshlrev_b32_e32 v38, 16, v118
	v_and_b32_e32 v39, 0xffff0000, v118
	v_lshlrev_b32_e32 v42, 16, v114
	v_and_b32_e32 v43, 0xffff0000, v114
	v_pk_fma_f32 v[36:37], v[36:37], v[42:43], v[38:39]
	v_add_f32_e32 v38, 1.0, v40
	v_add_f32_e32 v39, 1.0, v41
	v_rcp_f32_e32 v38, v38
	v_rcp_f32_e32 v39, v39
	v_lshlrev_b32_e32 v40, 16, v119
	v_and_b32_e32 v41, 0xffff0000, v119
	v_lshlrev_b32_e32 v42, 16, v115
	v_and_b32_e32 v43, 0xffff0000, v115
	v_pk_add_f32 v[28:29], v[28:29], v[76:77]
	v_pk_fma_f32 v[38:39], v[38:39], v[42:43], v[40:41]
	s_nop 1
	v_permlane16_swap_b32 v32, v36
	v_permlane16_swap_b32 v33, v37
	v_permlane16_swap_b32 v34, v38
	v_permlane16_swap_b32 v35, v39
	v_permlane32_swap_b32 v32, v36
	v_permlane32_swap_b32 v33, v37
	v_permlane32_swap_b32 v34, v38
	v_permlane32_swap_b32 v35, v39
	global_store_dwordx4 v[48:49], v[32:35], off offset:512
	global_store_dwordx4 v[48:49], v[36:39], off offset:576
	v_pk_add_f32 v[30:31], v[30:31], v[78:79]
	v_pk_add_f32 v[32:33], v[26:27], v[74:75]
	v_mul_f32_e32 v26, 0xbfb8aa3b, v28
	v_min_f32_e32 v26, 0x42fc0000, v26
	v_exp_f32_e32 v28, v26
	v_mul_f32_e32 v26, 0xbfb8aa3b, v29
	v_min_f32_e32 v26, 0x42fc0000, v26
	v_exp_f32_e32 v29, v26
	v_mul_f32_e32 v30, 0xbfb8aa3b, v30
	v_mul_f32_e32 v31, 0xbfb8aa3b, v31
	v_pk_add_f32 v[26:27], v[24:25], v[72:73]
	v_add_f32_e32 v24, 1.0, v28
	v_add_f32_e32 v25, 1.0, v29
	v_min_f32_e32 v30, 0x42fc0000, v30
	v_min_f32_e32 v31, 0x42fc0000, v31
	v_rcp_f32_e32 v24, v24
	v_rcp_f32_e32 v25, v25
	v_exp_f32_e32 v30, v30
	v_exp_f32_e32 v31, v31
	v_mul_f32_e32 v26, 0xbfb8aa3b, v26
	v_min_f32_e32 v26, 0x42fc0000, v26
	s_waitcnt vmcnt(14)
; DI float sigmoidf_(float x) { return __builtin_amdgcn_rcpf(1.f + __builtin_amdgcn_exp2f(fminf(-x * LOG2E, 126.f))); }
;     DI void operator()(const f32x4 (&acc)[2][2][4][2], const Unit& u, int wr, int wc, int fr, int fq) const {
;     ...
; #pragma unroll
;             for (int m = 0; m < 4; ++m)
; #pragma unroll
;                 for (int bj = 0; bj < 2; ++bj) {
;                     const size_t off = (size_t)(u.pm * 256 + ai * 128 + wr * 64 + m * 16 + fr) * DM + u.pn * 256 + bj * 128 + wc * 32 + 8 * fq;
;                     const u32x4 p = pw[m][bj], x = xw[m][bj];
;                     const f32x4 a0 = acc[ai][bj][m][0] + b0[bj], a1 = acc[ai][bj][m][1] + b1[bj];
;                     f32x4 x0, x1;
;                     x0[0] = bflo(x.x) + sigmoidf_(a0[0]) * bflo(p.x); x0[1] = bfhi(x.x) + sigmoidf_(a0[1]) * bfhi(p.x); x0[2] = bflo(x.y) + sigmoidf_(a0[2]) * bflo(p.y); x0[3] = bfhi(x.y) + sigmoidf_(a0[3]) * bfhi(p.y);
;                     x1[0] = bflo(x.z) + sigmoidf_(a1[0]) * bflo(p.z); x1[1] = bfhi(x.z) + sigmoidf_(a1[1]) * bfhi(p.z); x1[2] = bflo(x.w) + sigmoidf_(a1[2]) * bflo(p.w); x1[3] = bfhi(x.w) + sigmoidf_(a1[3]) * bfhi(p.w);
;                     *(f32x4*)(out + off) = x0; *(f32x4*)(out + off + 4) = x1;
	v_lshlrev_b32_e32 v28, 16, v108
	v_and_b32_e32 v29, 0xffff0000, v108
	v_lshlrev_b32_e32 v34, 16, v104
	v_and_b32_e32 v35, 0xffff0000, v104
	v_exp_f32_e32 v36, v26
	v_mul_f32_e32 v26, 0xbfb8aa3b, v27
	v_pk_fma_f32 v[24:25], v[24:25], v[34:35], v[28:29]
	v_add_f32_e32 v28, 1.0, v30
	v_add_f32_e32 v29, 1.0, v31
	v_min_f32_e32 v26, 0x42fc0000, v26
	v_rcp_f32_e32 v28, v28
	v_rcp_f32_e32 v29, v29
	v_exp_f32_e32 v37, v26
	v_lshlrev_b32_e32 v30, 16, v109
	v_and_b32_e32 v31, 0xffff0000, v109
	v_lshlrev_b32_e32 v34, 16, v105
	v_and_b32_e32 v35, 0xffff0000, v105
	v_mul_f32_e32 v32, 0xbfb8aa3b, v32
	v_mul_f32_e32 v33, 0xbfb8aa3b, v33
	v_pk_fma_f32 v[26:27], v[28:29], v[34:35], v[30:31]
	v_add_f32_e32 v28, 1.0, v36
	v_add_f32_e32 v29, 1.0, v37
	v_min_f32_e32 v32, 0x42fc0000, v32
	v_min_f32_e32 v33, 0x42fc0000, v33
	v_rcp_f32_e32 v28, v28
	v_rcp_f32_e32 v29, v29
	v_exp_f32_e32 v32, v32
	v_exp_f32_e32 v33, v33
	v_lshlrev_b32_e32 v30, 16, v110
	v_and_b32_e32 v31, 0xffff0000, v110
	v_lshlrev_b32_e32 v34, 16, v106
	v_and_b32_e32 v35, 0xffff0000, v106
	v_pk_fma_f32 v[28:29], v[28:29], v[34:35], v[30:31]
	v_add_f32_e32 v30, 1.0, v32
	v_add_f32_e32 v31, 1.0, v33
	v_rcp_f32_e32 v30, v30
	v_rcp_f32_e32 v31, v31
	v_lshlrev_b32_e32 v32, 16, v111
	v_and_b32_e32 v33, 0xffff0000, v111
	v_lshlrev_b32_e32 v34, 16, v107
	v_and_b32_e32 v35, 0xffff0000, v107
	v_pk_fma_f32 v[30:31], v[30:31], v[34:35], v[32:33]
	v_lshl_add_u64 v[32:33], v[138:139], 2, s[10:11]
	v_lshl_add_u64 v[32:33], v[32:33], 0, v[246:247]
	v_pk_add_f32 v[20:21], v[20:21], v[68:69]
	s_nop 1
	v_permlane16_swap_b32 v24, v28
	v_permlane16_swap_b32 v25, v29
	v_permlane16_swap_b32 v26, v30
	v_permlane16_swap_b32 v27, v31
	v_permlane32_swap_b32 v24, v28
	v_permlane32_swap_b32 v25, v29
	v_permlane32_swap_b32 v26, v30
	v_permlane32_swap_b32 v27, v31
	global_store_dwordx4 v[32:33], v[24:27], off
	global_store_dwordx4 v[32:33], v[28:31], off offset:64
	v_pk_add_f32 v[22:23], v[22:23], v[70:71]
	v_pk_add_f32 v[24:25], v[18:19], v[66:67]
	v_mul_f32_e32 v18, 0xbfb8aa3b, v20
	v_min_f32_e32 v18, 0x42fc0000, v18
	v_exp_f32_e32 v20, v18
	v_mul_f32_e32 v18, 0xbfb8aa3b, v21
	v_min_f32_e32 v18, 0x42fc0000, v18
	v_exp_f32_e32 v21, v18
	v_mul_f32_e32 v22, 0xbfb8aa3b, v22
	v_mul_f32_e32 v23, 0xbfb8aa3b, v23
	v_pk_add_f32 v[18:19], v[16:17], v[64:65]
	v_add_f32_e32 v16, 1.0, v20
	v_add_f32_e32 v17, 1.0, v21
	v_min_f32_e32 v22, 0x42fc0000, v22
	v_min_f32_e32 v23, 0x42fc0000, v23
	v_rcp_f32_e32 v16, v16
	v_rcp_f32_e32 v17, v17
	v_exp_f32_e32 v22, v22
	v_exp_f32_e32 v23, v23
	v_mul_f32_e32 v18, 0xbfb8aa3b, v18
	v_min_f32_e32 v18, 0x42fc0000, v18
	s_waitcnt vmcnt(14)
	v_lshlrev_b32_e32 v20, 16, v100
	v_and_b32_e32 v21, 0xffff0000, v100
	v_lshlrev_b32_e32 v26, 16, v96
	v_and_b32_e32 v27, 0xffff0000, v96
	v_exp_f32_e32 v28, v18
	v_mul_f32_e32 v18, 0xbfb8aa3b, v19
	v_pk_fma_f32 v[16:17], v[16:17], v[26:27], v[20:21]
	v_add_f32_e32 v20, 1.0, v22
	v_add_f32_e32 v21, 1.0, v23
	v_min_f32_e32 v18, 0x42fc0000, v18
	v_rcp_f32_e32 v20, v20
	v_rcp_f32_e32 v21, v21
	v_exp_f32_e32 v29, v18
	v_lshlrev_b32_e32 v22, 16, v101
	v_and_b32_e32 v23, 0xffff0000, v101
	v_lshlrev_b32_e32 v26, 16, v97
	v_and_b32_e32 v27, 0xffff0000, v97
	v_mul_f32_e32 v24, 0xbfb8aa3b, v24
	v_mul_f32_e32 v25, 0xbfb8aa3b, v25
	v_pk_fma_f32 v[18:19], v[20:21], v[26:27], v[22:23]
	v_add_f32_e32 v20, 1.0, v28
	v_add_f32_e32 v21, 1.0, v29
	v_min_f32_e32 v24, 0x42fc0000, v24
	v_min_f32_e32 v25, 0x42fc0000, v25
	v_rcp_f32_e32 v20, v20
	v_rcp_f32_e32 v21, v21
	v_exp_f32_e32 v24, v24
	v_exp_f32_e32 v25, v25
	v_lshlrev_b32_e32 v22, 16, v102
	v_and_b32_e32 v23, 0xffff0000, v102
	v_lshlrev_b32_e32 v26, 16, v98
	v_and_b32_e32 v27, 0xffff0000, v98
	v_pk_fma_f32 v[20:21], v[20:21], v[26:27], v[22:23]
	v_add_f32_e32 v22, 1.0, v24
	v_add_f32_e32 v23, 1.0, v25
	v_rcp_f32_e32 v22, v22
	v_rcp_f32_e32 v23, v23
	v_lshlrev_b32_e32 v24, 16, v103
	v_and_b32_e32 v25, 0xffff0000, v103
	v_lshlrev_b32_e32 v26, 16, v99
	v_and_b32_e32 v27, 0xffff0000, v99
	v_pk_add_f32 v[12:13], v[12:13], v[76:77]
	v_pk_fma_f32 v[22:23], v[22:23], v[26:27], v[24:25]
	s_nop 1
	v_permlane16_swap_b32 v16, v20
	v_permlane16_swap_b32 v17, v21
	v_permlane16_swap_b32 v18, v22
	v_permlane16_swap_b32 v19, v23
	v_permlane32_swap_b32 v16, v20
	v_permlane32_swap_b32 v17, v21
	v_permlane32_swap_b32 v18, v22
	v_permlane32_swap_b32 v19, v23
	global_store_dwordx4 v[32:33], v[16:19], off offset:512
	global_store_dwordx4 v[32:33], v[20:23], off offset:576
	v_pk_add_f32 v[14:15], v[14:15], v[78:79]
	v_pk_add_f32 v[16:17], v[10:11], v[74:75]
	v_mul_f32_e32 v10, 0xbfb8aa3b, v12
	v_min_f32_e32 v10, 0x42fc0000, v10
	v_exp_f32_e32 v12, v10
	v_mul_f32_e32 v10, 0xbfb8aa3b, v13
	v_min_f32_e32 v10, 0x42fc0000, v10
	v_exp_f32_e32 v13, v10
	v_mul_f32_e32 v14, 0xbfb8aa3b, v14
	v_mul_f32_e32 v15, 0xbfb8aa3b, v15
	v_pk_add_f32 v[10:11], v[8:9], v[72:73]
	v_add_f32_e32 v8, 1.0, v12
	v_add_f32_e32 v9, 1.0, v13
	v_min_f32_e32 v14, 0x42fc0000, v14
	v_min_f32_e32 v15, 0x42fc0000, v15
	v_rcp_f32_e32 v8, v8
	v_rcp_f32_e32 v9, v9
	v_exp_f32_e32 v14, v14
	v_exp_f32_e32 v15, v15
	v_mul_f32_e32 v10, 0xbfb8aa3b, v10
	v_min_f32_e32 v10, 0x42fc0000, v10
	s_waitcnt vmcnt(14)
; DI float sigmoidf_(float x) { return __builtin_amdgcn_rcpf(1.f + __builtin_amdgcn_exp2f(fminf(-x * LOG2E, 126.f))); }
;     DI void operator()(const f32x4 (&acc)[2][2][4][2], const Unit& u, int wr, int wc, int fr, int fq) const {
;     ...
; #pragma unroll
;             for (int m = 0; m < 4; ++m)
; #pragma unroll
;                 for (int bj = 0; bj < 2; ++bj) {
;                     const size_t off = (size_t)(u.pm * 256 + ai * 128 + wr * 64 + m * 16 + fr) * DM + u.pn * 256 + bj * 128 + wc * 32 + 8 * fq;
;                     const u32x4 p = pw[m][bj], x = xw[m][bj];
;                     const f32x4 a0 = acc[ai][bj][m][0] + b0[bj], a1 = acc[ai][bj][m][1] + b1[bj];
;                     f32x4 x0, x1;
;                     x0[0] = bflo(x.x) + sigmoidf_(a0[0]) * bflo(p.x); x0[1] = bfhi(x.x) + sigmoidf_(a0[1]) * bfhi(p.x); x0[2] = bflo(x.y) + sigmoidf_(a0[2]) * bflo(p.y); x0[3] = bfhi(x.y) + sigmoidf_(a0[3]) * bfhi(p.y);
;                     x1[0] = bflo(x.z) + sigmoidf_(a1[0]) * bflo(p.z); x1[1] = bfhi(x.z) + sigmoidf_(a1[1]) * bfhi(p.z); x1[2] = bflo(x.w) + sigmoidf_(a1[2]) * bflo(p.w); x1[3] = bfhi(x.w) + sigmoidf_(a1[3]) * bfhi(p.w);
;                     *(f32x4*)(out + off) = x0; *(f32x4*)(out + off + 4) = x1;
	v_lshlrev_b32_e32 v12, 16, v92
	v_and_b32_e32 v13, 0xffff0000, v92
	v_lshlrev_b32_e32 v18, 16, v88
	v_and_b32_e32 v19, 0xffff0000, v88
	v_exp_f32_e32 v20, v10
	v_mul_f32_e32 v10, 0xbfb8aa3b, v11
	v_pk_fma_f32 v[8:9], v[8:9], v[18:19], v[12:13]
	v_add_f32_e32 v12, 1.0, v14
	v_add_f32_e32 v13, 1.0, v15
	v_min_f32_e32 v10, 0x42fc0000, v10
	v_rcp_f32_e32 v12, v12
	v_rcp_f32_e32 v13, v13
	v_exp_f32_e32 v21, v10
	v_lshlrev_b32_e32 v14, 16, v93
	v_and_b32_e32 v15, 0xffff0000, v93
	v_lshlrev_b32_e32 v18, 16, v89
	v_and_b32_e32 v19, 0xffff0000, v89
	v_mul_f32_e32 v16, 0xbfb8aa3b, v16
	v_mul_f32_e32 v17, 0xbfb8aa3b, v17
	v_pk_fma_f32 v[10:11], v[12:13], v[18:19], v[14:15]
	v_add_f32_e32 v12, 1.0, v20
	v_add_f32_e32 v13, 1.0, v21
	v_min_f32_e32 v16, 0x42fc0000, v16
	v_min_f32_e32 v17, 0x42fc0000, v17
	v_rcp_f32_e32 v12, v12
	v_rcp_f32_e32 v13, v13
	v_exp_f32_e32 v16, v16
	v_exp_f32_e32 v17, v17
	v_lshlrev_b32_e32 v14, 16, v94
	v_and_b32_e32 v15, 0xffff0000, v94
	v_lshlrev_b32_e32 v18, 16, v90
	v_and_b32_e32 v19, 0xffff0000, v90
	v_pk_fma_f32 v[12:13], v[12:13], v[18:19], v[14:15]
	v_add_f32_e32 v14, 1.0, v16
	v_add_f32_e32 v15, 1.0, v17
	v_rcp_f32_e32 v14, v14
	v_rcp_f32_e32 v15, v15
	v_lshlrev_b32_e32 v16, 16, v95
	v_and_b32_e32 v17, 0xffff0000, v95
	v_lshlrev_b32_e32 v18, 16, v91
	v_and_b32_e32 v19, 0xffff0000, v91
	v_pk_fma_f32 v[14:15], v[14:15], v[18:19], v[16:17]
	v_lshl_add_u64 v[16:17], v[136:137], 2, s[10:11]
	v_lshl_add_u64 v[16:17], v[16:17], 0, v[246:247]
	v_pk_add_f32 v[4:5], v[4:5], v[68:69]
	s_nop 1
	v_permlane16_swap_b32 v8, v12
	v_permlane16_swap_b32 v9, v13
	v_permlane16_swap_b32 v10, v14
	v_permlane16_swap_b32 v11, v15
	v_permlane32_swap_b32 v8, v12
	v_permlane32_swap_b32 v9, v13
	v_permlane32_swap_b32 v10, v14
	v_permlane32_swap_b32 v11, v15
	global_store_dwordx4 v[16:17], v[8:11], off
	global_store_dwordx4 v[16:17], v[12:15], off offset:64
	v_pk_add_f32 v[6:7], v[6:7], v[70:71]
	v_pk_add_f32 v[8:9], v[2:3], v[66:67]
	v_mul_f32_e32 v2, 0xbfb8aa3b, v4
	v_min_f32_e32 v2, 0x42fc0000, v2
	v_exp_f32_e32 v4, v2
	v_mul_f32_e32 v2, 0xbfb8aa3b, v5
	v_min_f32_e32 v2, 0x42fc0000, v2
	v_exp_f32_e32 v5, v2
	v_mul_f32_e32 v6, 0xbfb8aa3b, v6
	v_mul_f32_e32 v7, 0xbfb8aa3b, v7
	v_pk_add_f32 v[2:3], v[0:1], v[64:65]
	v_add_f32_e32 v0, 1.0, v4
	v_add_f32_e32 v1, 1.0, v5
	v_min_f32_e32 v6, 0x42fc0000, v6
	v_min_f32_e32 v7, 0x42fc0000, v7
	v_rcp_f32_e32 v0, v0
	v_rcp_f32_e32 v1, v1
	v_exp_f32_e32 v6, v6
	v_exp_f32_e32 v7, v7
	v_mul_f32_e32 v2, 0xbfb8aa3b, v2
	v_min_f32_e32 v2, 0x42fc0000, v2
	s_waitcnt vmcnt(14)
	v_lshlrev_b32_e32 v4, 16, v84
	v_and_b32_e32 v5, 0xffff0000, v84
	v_lshlrev_b32_e32 v10, 16, v80
	v_and_b32_e32 v11, 0xffff0000, v80
	v_exp_f32_e32 v12, v2
	v_mul_f32_e32 v2, 0xbfb8aa3b, v3
	v_pk_fma_f32 v[0:1], v[0:1], v[10:11], v[4:5]
	v_add_f32_e32 v4, 1.0, v6
	v_add_f32_e32 v5, 1.0, v7
	v_min_f32_e32 v2, 0x42fc0000, v2
	v_rcp_f32_e32 v4, v4
	v_rcp_f32_e32 v5, v5
	v_exp_f32_e32 v13, v2
	v_lshlrev_b32_e32 v6, 16, v85
	v_and_b32_e32 v7, 0xffff0000, v85
	v_lshlrev_b32_e32 v10, 16, v81
	v_and_b32_e32 v11, 0xffff0000, v81
	v_mul_f32_e32 v8, 0xbfb8aa3b, v8
	v_mul_f32_e32 v9, 0xbfb8aa3b, v9
	v_pk_fma_f32 v[2:3], v[4:5], v[10:11], v[6:7]
	v_add_f32_e32 v4, 1.0, v12
	v_add_f32_e32 v5, 1.0, v13
	v_min_f32_e32 v8, 0x42fc0000, v8
	v_min_f32_e32 v9, 0x42fc0000, v9
	v_rcp_f32_e32 v4, v4
	v_rcp_f32_e32 v5, v5
	v_exp_f32_e32 v8, v8
	v_exp_f32_e32 v9, v9
	v_lshlrev_b32_e32 v6, 16, v86
	v_and_b32_e32 v7, 0xffff0000, v86
	v_lshlrev_b32_e32 v10, 16, v82
	v_and_b32_e32 v11, 0xffff0000, v82
	v_pk_fma_f32 v[4:5], v[4:5], v[10:11], v[6:7]
	v_add_f32_e32 v6, 1.0, v8
	v_add_f32_e32 v7, 1.0, v9
	v_rcp_f32_e32 v6, v6
	v_rcp_f32_e32 v7, v7
	v_lshlrev_b32_e32 v8, 16, v87
	v_and_b32_e32 v9, 0xffff0000, v87
	v_lshlrev_b32_e32 v10, 16, v83
	v_and_b32_e32 v11, 0xffff0000, v83
	v_pk_fma_f32 v[6:7], v[6:7], v[10:11], v[8:9]
	s_nop 1
	v_permlane16_swap_b32 v0, v4
	v_permlane16_swap_b32 v1, v5
	v_permlane16_swap_b32 v2, v6
	v_permlane16_swap_b32 v3, v7
	v_permlane32_swap_b32 v0, v4
	v_permlane32_swap_b32 v1, v5
	v_permlane32_swap_b32 v2, v6
	v_permlane32_swap_b32 v3, v7
	global_store_dwordx4 v[16:17], v[0:3], off offset:512
	global_store_dwordx4 v[16:17], v[4:7], off offset:576
	s_cbranch_vccnz .LBB0_1651
	s_and_b64 vcc, exec, s[0:1]
	s_cbranch_vccnz .LBB0_1650
	s_barrier
	s_branch .LBB0_1650
